# G1 (mLSTM in-proj) and RG-LRU in-proj epilogues also read cached per-panel row rstd instead of reloading ssq partials and waiting vmcnt(0) each row group
# baseline (speedup 1.0000x reference)
;     __device__ bool next(int i, Unit& u) const { if (!StaticOrder::next(i, u)) return false; u.aoff = (u.pn >> 1) * 512; return true; }
;     __host__ __device__ bool next(int i, Unit& u) const {
;         const long L = (long)i * G + c; if (L >= nwg) return false;
;         int wgid = (int)L; { const int q = nwg / NXCD, r = nwg % NXCD, xcd = wgid % NXCD, off = wgid / NXCD; wgid = (xcd < r ? xcd * (q + 1) : r * (q + 1) + (xcd - r) * q) + off; }
;         const int nig = WGM * nN, gid = wgid / nig, fm = gid * WGM, gsz = (nM - fm) < WGM ? (nM - fm) : WGM;
;         u.pm = fm + ((wgid % nig) % gsz); u.pn = (wgid % nig) / gsz; u.aoff = 0; return true;
; template <class Epi, class Sched, bool ALIGN_EPI = false, bool SP2 = false>
; __device__ __forceinline__ void gemm_phase(PG8_LAS unsigned char* lds, const Gemm g, const Sched& S, const Epi& E) {
;     ...
;     Unit cur, nxt; int ui = 0;
;     if (!S.next(0, cur)) return;
.LBB0_277:
	s_mov_b32 s98, -1
	s_cmpk_lt_i32 s2, 0x600
	s_cselect_b64 s[4:5], -1, 0
	s_mov_b64 s[6:7], s[92:93]
	s_waitcnt vmcnt(0)
	v_mov_b32_e32 v8, v167
	s_and_b64 vcc, exec, s[4:5]
	s_cbranch_vccz .LBB0_279
	s_ashr_i32 s0, s2, 31
	s_lshr_b32 s0, s0, 29
	s_add_i32 s0, s2, s0
	s_ashr_i32 s1, s0, 3
	s_and_b32 s0, s0, -8
	s_sub_i32 s0, s2, s0
	s_cmp_lt_i32 s0, 0
	s_movk_i32 s3, 0xc1
	s_cselect_b32 s3, s3, 0xc0
	s_mul_i32 s0, s0, s3
	s_add_i32 s0, s0, s1
	s_mul_hi_i32 s1, s0, 0x2aaaaaab
	s_lshr_b32 s3, s1, 31
	s_ashr_i32 s1, s1, 5
	s_add_i32 s1, s1, s3
	s_lshl_b32 s3, s1, 3
	s_mulk_i32 s1, 0xc0
	s_sub_i32 s0, s0, s1
	s_sext_i32_i16 s1, s0
	s_bfe_u32 s1, s1, 0x3001c
	s_add_i32 s1, s0, s1
	s_sext_i32_i16 s9, s1
	s_and_b32 s1, s1, 0xfff8
	s_sub_i32 s0, s0, s1
	s_sext_i32_i16 s0, s0
	s_add_i32 s8, s3, s0
	s_ashr_i32 s10, s9, 3

; __device__ __forceinline__ float shx(float v, int mask, int lane) { return __int_as_float(__builtin_amdgcn_ds_bpermute((lane ^ mask) << 2, __float_as_int(v))); }
; __device__ __forceinline__ float row_rstd(const float* ssqp, int row, int fr, int fq) {
;     const f32x4 p0 = *(const f32x4*)(ssqp + (size_t)row * 32 + fq * 8), p1 = *(const f32x4*)(ssqp + (size_t)row * 32 + fq * 8 + 4);
;     float t = ((p0[0] + p0[1]) + (p0[2] + p0[3])) + ((p1[0] + p1[1]) + (p1[2] + p1[3])); const int ln = fr + 16 * fq;
;     t += shx(t, 16, ln); t += shx(t, 32, ln);
;     return rsqrtf(t * (1.0f / 2048.0f) + RMS_EPS);
; }
;     __device__ __forceinline__ void operator()(const f32x4 (&acc)[2][2][4][2], const Unit& u, int wr, int wc, int fr, int fq) const {
;     ...
;             for (int m = 0; m < 4; ++m) { const int row = row0 + ai * HALF + m * 16; const float rs = row_rstd(ssq, row, fr, fq);
.LBB0_291:
	s_cmp_eq_u32 s8, s98
	s_cbranch_scc1 .Lg1_have
	v_and_b32_e32 v144, 15, v167
	v_lshrrev_b32_e32 v145, 4, v167
	s_lshl_b32 s4, s8, 8
	s_add_i32 s4, s4, s78
	v_or_b32_e32 v146, s4, v144
	v_lshlrev_b32_e32 v147, 7, v146
	v_lshl_add_u32 v147, v145, 5, v147
	v_add_u32_e32 v163, 0x1000, v147
	v_add_u32_e32 v164, 0x4000, v147
	v_add_u32_e32 v165, 0x5000, v147
	global_load_dwordx4 v[168:171], v147, s[20:21]
	global_load_dwordx4 v[172:175], v147, s[20:21] offset:16
	global_load_dwordx4 v[176:179], v147, s[20:21] offset:2048
	global_load_dwordx4 v[180:183], v147, s[20:21] offset:2064
	global_load_dwordx4 v[184:187], v163, s[20:21]
	global_load_dwordx4 v[188:191], v163, s[20:21] offset:16
	global_load_dwordx4 v[192:195], v163, s[20:21] offset:2048
	global_load_dwordx4 v[196:199], v163, s[20:21] offset:2064
	global_load_dwordx4 v[200:203], v164, s[20:21]
	global_load_dwordx4 v[204:207], v164, s[20:21] offset:16
	global_load_dwordx4 v[208:211], v164, s[20:21] offset:2048
	global_load_dwordx4 v[212:215], v164, s[20:21] offset:2064
	global_load_dwordx4 v[216:219], v165, s[20:21]
	global_load_dwordx4 v[220:223], v165, s[20:21] offset:16
	global_load_dwordx4 v[224:227], v165, s[20:21] offset:2048
	global_load_dwordx4 v[228:231], v165, s[20:21] offset:2064
	v_xor_b32_e32 v144, 16, v167
	v_xor_b32_e32 v145, 32, v167
	v_lshlrev_b32_e32 v144, 2, v144
	v_lshlrev_b32_e32 v145, 2, v145
	s_waitcnt vmcnt(0)
	v_add_f32_e32 v168, v168, v169
	v_add_f32_e32 v176, v176, v177
	v_add_f32_e32 v184, v184, v185
	v_add_f32_e32 v192, v192, v193
	v_add_f32_e32 v200, v200, v201
	v_add_f32_e32 v208, v208, v209
	v_add_f32_e32 v216, v216, v217
	v_add_f32_e32 v224, v224, v225
	v_add_f32_e32 v170, v170, v171
	v_add_f32_e32 v178, v178, v179
	v_add_f32_e32 v186, v186, v187
	v_add_f32_e32 v194, v194, v195
	v_add_f32_e32 v202, v202, v203
	v_add_f32_e32 v210, v210, v211
	v_add_f32_e32 v218, v218, v219
	v_add_f32_e32 v226, v226, v227
	v_add_f32_e32 v172, v172, v173
	v_add_f32_e32 v180, v180, v181
	v_add_f32_e32 v188, v188, v189
	v_add_f32_e32 v196, v196, v197
	v_add_f32_e32 v204, v204, v205
	v_add_f32_e32 v212, v212, v213
	v_add_f32_e32 v220, v220, v221
	v_add_f32_e32 v228, v228, v229
	v_add_f32_e32 v174, v174, v175
	v_add_f32_e32 v182, v182, v183
	v_add_f32_e32 v190, v190, v191
	v_add_f32_e32 v198, v198, v199
	v_add_f32_e32 v206, v206, v207
	v_add_f32_e32 v214, v214, v215
	v_add_f32_e32 v222, v222, v223
	v_add_f32_e32 v230, v230, v231
	v_add_f32_e32 v168, v168, v170
	v_add_f32_e32 v176, v176, v178
	v_add_f32_e32 v184, v184, v186
	v_add_f32_e32 v192, v192, v194
	v_add_f32_e32 v200, v200, v202
	v_add_f32_e32 v208, v208, v210
	v_add_f32_e32 v216, v216, v218
	v_add_f32_e32 v224, v224, v226
	v_add_f32_e32 v172, v172, v174
	v_add_f32_e32 v180, v180, v182
	v_add_f32_e32 v188, v188, v190
	v_add_f32_e32 v196, v196, v198
	v_add_f32_e32 v204, v204, v206
	v_add_f32_e32 v212, v212, v214
	v_add_f32_e32 v220, v220, v222
	v_add_f32_e32 v228, v228, v230
	v_add_f32_e32 v168, v168, v172
	v_add_f32_e32 v176, v176, v180
	v_add_f32_e32 v184, v184, v188
	v_add_f32_e32 v192, v192, v196
	v_add_f32_e32 v200, v200, v204
	v_add_f32_e32 v208, v208, v212
	v_add_f32_e32 v216, v216, v220
	v_add_f32_e32 v224, v224, v228
	ds_bpermute_b32 v242, v144, v168
	ds_bpermute_b32 v243, v144, v176
	ds_bpermute_b32 v244, v144, v184
	ds_bpermute_b32 v245, v144, v192
	ds_bpermute_b32 v246, v144, v200
	ds_bpermute_b32 v247, v144, v208
	ds_bpermute_b32 v248, v144, v216
	ds_bpermute_b32 v249, v144, v224
	s_waitcnt lgkmcnt(0)
	v_add_f32_e32 v168, v168, v242
	v_add_f32_e32 v176, v176, v243
	v_add_f32_e32 v184, v184, v244
	v_add_f32_e32 v192, v192, v245
	v_add_f32_e32 v200, v200, v246
	v_add_f32_e32 v208, v208, v247
	v_add_f32_e32 v216, v216, v248
	v_add_f32_e32 v224, v224, v249
	ds_bpermute_b32 v242, v145, v168
	ds_bpermute_b32 v243, v145, v176
	ds_bpermute_b32 v244, v145, v184
	ds_bpermute_b32 v245, v145, v192
	ds_bpermute_b32 v246, v145, v200
	ds_bpermute_b32 v247, v145, v208
	ds_bpermute_b32 v248, v145, v216
	ds_bpermute_b32 v249, v145, v224
	s_waitcnt lgkmcnt(0)
	v_add_f32_e32 v168, v168, v242
	v_add_f32_e32 v176, v176, v243
	v_add_f32_e32 v184, v184, v244
	v_add_f32_e32 v192, v192, v245
	v_add_f32_e32 v200, v200, v246
	v_add_f32_e32 v208, v208, v247
	v_add_f32_e32 v216, v216, v248
	v_add_f32_e32 v224, v224, v249
	v_fmamk_f32 v168, v168, 0x3a000000, v162
	v_fmamk_f32 v176, v176, 0x3a000000, v162
	v_fmamk_f32 v184, v184, 0x3a000000, v162
	v_fmamk_f32 v192, v192, 0x3a000000, v162
	v_fmamk_f32 v200, v200, 0x3a000000, v162
	v_fmamk_f32 v208, v208, 0x3a000000, v162
	v_fmamk_f32 v216, v216, 0x3a000000, v162
	v_fmamk_f32 v224, v224, 0x3a000000, v162
	v_rsq_f32_e32 v169, v168
	v_rsq_f32_e32 v177, v176
	v_rsq_f32_e32 v185, v184
	v_rsq_f32_e32 v193, v192
	v_rsq_f32_e32 v201, v200
	v_rsq_f32_e32 v209, v208
	v_rsq_f32_e32 v217, v216
	v_rsq_f32_e32 v225, v224
	v_mov_b32_e32 v226, v169
	v_mov_b32_e32 v227, v177
	v_mov_b32_e32 v228, v185
	v_mov_b32_e32 v229, v193
	v_mov_b32_e32 v230, v201
	v_mov_b32_e32 v231, v209
	v_mov_b32_e32 v232, v217
	v_mov_b32_e32 v233, v225
	s_mov_b32 s98, s8

; __device__ __forceinline__ unsigned cvt_pk_bf16(float lo, float hi) { unsigned r; asm volatile("v_cvt_pk_bf16_f32 %0, %1, %2" : "=v"(r) : "v"(lo), "v"(hi)); return r; }
;     __device__ __forceinline__ void operator()(const f32x4 (&acc)[2][2][4][2], const Unit& u, int wr, int wc, int fr, int fq) const {
;     ...
;             for (int m = 0; m < 4; ++m) { const int row = row0 + ai * HALF + m * 16; const float rs = row_rstd(ssq, row, fr, fq);
;                 bf16_t* rowp = base + (size_t)row * ldc + col0;
; #pragma unroll
;                 for (int bj = 0; bj < 2; ++bj) { f32x4 v0, v1;
;                     if (sig) { const float nr = -1.4426950408889634f * rs;
; #pragma unroll
;                         for (int j = 0; j < 4; ++j) { v0[j] = __builtin_amdgcn_rcpf(1.0f + __builtin_amdgcn_exp2f(acc[ai][bj][m][0][j] * nr)); v1[j] = __builtin_amdgcn_rcpf(1.0f + __builtin_amdgcn_exp2f(acc[ai][bj][m][1][j] * nr)); } }
;                     else { v0 = acc[ai][bj][m][0] * rs; v1 = acc[ai][bj][m][1] * rs; }
;                     u32x4 w; w.x = cvt_pk_bf16(v0[0], v0[1]); w.y = cvt_pk_bf16(v0[2], v0[3]); w.z = cvt_pk_bf16(v1[0], v1[1]); w.w = cvt_pk_bf16(v1[2], v1[3]);
;                     *(u32x4*)(rowp + bj * HALF) = w; }
.LBB0_303:
	s_lshl_b32 s4, s8, 8
	v_and_b32_e32 v156, 15, v144
	s_add_i32 s4, s4, s78
	v_or_b32_e32 v146, s4, v156
	v_ashrrev_i32_e32 v157, 4, v144
	v_ashrrev_i32_e32 v147, 31, v146
	v_lshlrev_b32_e32 v144, 3, v157
	v_lshlrev_b64 v[148:149], 7, v[146:147]
	v_ashrrev_i32_e32 v145, 31, v144
	v_lshl_add_u64 v[148:149], s[20:21], 0, v[148:149]
	v_lshl_add_u64 v[152:153], v[144:145], 2, v[148:149]
	s_nop 0
	v_lshlrev_b32_e32 v164, 6, v157
	v_lshlrev_b32_e32 v165, 2, v156
	v_bitop3_b32 v163, v164, 64, v165 bitop3:0x36
	v_bitop3_b32 v164, v164, s57, v165 bitop3:0x36
	s_xor_b64 s[10:11], s[40:41], -1
	s_and_b64 s[8:9], exec, s[10:11]
	s_mov_b64 s[50:51], -1
	v_mov_b32_e32 v156, v148
	v_mov_b32_e32 v157, v152
	v_mov_b32_e32 v152, v149
	v_mov_b32_e32 v148, v150
	v_mov_b32_e32 v149, v154
	v_mov_b32_e32 v154, v151
	v_pk_add_f32 v[150:151], v[156:157], v[152:153]
	v_pk_add_f32 v[148:149], v[148:149], v[154:155]
	s_nop 0
	v_pk_add_f32 v[148:149], v[150:151], v[148:149]
	s_nop 0
	v_add_f32_e32 v148, v148, v149
	v_add_f32_e32 v148, v148, v149
	v_add_f32_e32 v148, v148, v149
	v_fmamk_f32 v148, v148, 0x3a000000, v162
	v_mul_f32_e32 v149, 0x4b800000, v148
	v_cmp_gt_f32_e32 vcc, s58, v148
	s_nop 1
	v_cndmask_b32_e32 v148, v148, v149, vcc
	s_nop 0
	v_mov_b32_e32 v148, v226
	v_mov_b32_e32 v149, v148
	s_mov_b64 vcc, s[8:9]
	s_cbranch_vccz .LBB0_305
	v_mov_b32_e32 v152, v148
	v_mov_b32_e32 v153, v148
	v_pk_mul_f32 v[154:155], v[126:127], v[152:153]
	v_pk_mul_f32 v[150:151], v[124:125], v[148:149]
	v_pk_mul_f32 v[156:157], v[122:123], v[152:153]
	v_pk_mul_f32 v[152:153], v[120:121], v[148:149]
	s_mov_b64 s[50:51], 0

; __device__ __forceinline__ unsigned cvt_pk_bf16(float lo, float hi) { unsigned r; asm volatile("v_cvt_pk_bf16_f32 %0, %1, %2" : "=v"(r) : "v"(lo), "v"(hi)); return r; }
;     __device__ __forceinline__ void operator()(const f32x4 (&acc)[2][2][4][2], const Unit& u, int wr, int wc, int fr, int fq) const {
;     ...
;             for (int m = 0; m < 4; ++m) { const int row = row0 + ai * HALF + m * 16; const float rs = row_rstd(ssq, row, fr, fq);
;                 bf16_t* rowp = base + (size_t)row * ldc + col0;
; #pragma unroll
;                 for (int bj = 0; bj < 2; ++bj) { f32x4 v0, v1;
;                     if (sig) { const float nr = -1.4426950408889634f * rs;
; #pragma unroll
;                         for (int j = 0; j < 4; ++j) { v0[j] = __builtin_amdgcn_rcpf(1.0f + __builtin_amdgcn_exp2f(acc[ai][bj][m][0][j] * nr)); v1[j] = __builtin_amdgcn_rcpf(1.0f + __builtin_amdgcn_exp2f(acc[ai][bj][m][1][j] * nr)); } }
;                     else { v0 = acc[ai][bj][m][0] * rs; v1 = acc[ai][bj][m][1] * rs; }
;                     u32x4 w; w.x = cvt_pk_bf16(v0[0], v0[1]); w.y = cvt_pk_bf16(v0[2], v0[3]); w.z = cvt_pk_bf16(v1[0], v1[1]); w.w = cvt_pk_bf16(v1[2], v1[3]);
;                     *(u32x4*)(rowp + bj * HALF) = w; }
.LBB0_311:
	v_cvt_pk_bf16_f32 v112, v124, v125
	v_cvt_pk_bf16_f32 v113, v150, v151
	v_cvt_pk_bf16_f32 v114, v126, v127
	v_cvt_pk_bf16_f32 v115, v152, v153
	global_store_dwordx4 v[122:123], v[112:115], off offset:256
	s_and_b64 vcc, exec, s[8:9]
	s_nop 0
	v_or_b32_e32 v112, 16, v146
	v_ashrrev_i32_e32 v113, 31, v112
	v_lshlrev_b64 v[114:115], 7, v[112:113]
	v_lshl_add_u64 v[114:115], s[20:21], 0, v[114:115]
	v_lshl_add_u64 v[118:119], v[144:145], 2, v[114:115]
	v_mov_b32_e32 v118, v114
	v_mov_b32_e32 v119, v122
	v_mov_b32_e32 v122, v115
	v_mov_b32_e32 v114, v116
	v_mov_b32_e32 v115, v124
	v_mov_b32_e32 v124, v117
	v_pk_add_f32 v[116:117], v[118:119], v[122:123]
	v_pk_add_f32 v[114:115], v[114:115], v[124:125]
	s_nop 0
	v_pk_add_f32 v[114:115], v[116:117], v[114:115]
	s_nop 0
	v_add_f32_e32 v114, v114, v115
	v_add_f32_e32 v114, v114, v115
	v_add_f32_e32 v114, v114, v115
	v_fmamk_f32 v114, v114, 0x3a000000, v162
	v_mul_f32_e32 v115, 0x4b800000, v114
	v_cmp_gt_f32_e64 s[10:11], s58, v114
	s_nop 1
	v_cndmask_b32_e64 v114, v114, v115, s[10:11]
	s_nop 0
	v_mov_b32_e32 v114, v227
	v_mov_b32_e32 v115, v114
	s_mov_b64 s[10:11], -1
	s_cbranch_vccnz .LBB0_313
	v_mov_b32_e32 v118, v114
	v_mov_b32_e32 v119, v114
	v_pk_mul_f32 v[122:123], v[110:111], v[118:119]
	v_pk_mul_f32 v[116:117], v[108:109], v[114:115]
	v_pk_mul_f32 v[124:125], v[106:107], v[118:119]
	v_pk_mul_f32 v[118:119], v[104:105], v[114:115]
	s_mov_b64 s[10:11], 0

; __device__ __forceinline__ unsigned cvt_pk_bf16(float lo, float hi) { unsigned r; asm volatile("v_cvt_pk_bf16_f32 %0, %1, %2" : "=v"(r) : "v"(lo), "v"(hi)); return r; }
;     __device__ __forceinline__ void operator()(const f32x4 (&acc)[2][2][4][2], const Unit& u, int wr, int wc, int fr, int fq) const {
;     ...
;             for (int m = 0; m < 4; ++m) { const int row = row0 + ai * HALF + m * 16; const float rs = row_rstd(ssq, row, fr, fq);
;                 bf16_t* rowp = base + (size_t)row * ldc + col0;
; #pragma unroll
;                 for (int bj = 0; bj < 2; ++bj) { f32x4 v0, v1;
;                     if (sig) { const float nr = -1.4426950408889634f * rs;
; #pragma unroll
;                         for (int j = 0; j < 4; ++j) { v0[j] = __builtin_amdgcn_rcpf(1.0f + __builtin_amdgcn_exp2f(acc[ai][bj][m][0][j] * nr)); v1[j] = __builtin_amdgcn_rcpf(1.0f + __builtin_amdgcn_exp2f(acc[ai][bj][m][1][j] * nr)); } }
;                     else { v0 = acc[ai][bj][m][0] * rs; v1 = acc[ai][bj][m][1] * rs; }
;                     u32x4 w; w.x = cvt_pk_bf16(v0[0], v0[1]); w.y = cvt_pk_bf16(v0[2], v0[3]); w.z = cvt_pk_bf16(v1[0], v1[1]); w.w = cvt_pk_bf16(v1[2], v1[3]);
;                     *(u32x4*)(rowp + bj * HALF) = w; }
.LBB0_319:
	v_cvt_pk_bf16_f32 v96, v106, v107
	v_cvt_pk_bf16_f32 v97, v110, v111
	v_cvt_pk_bf16_f32 v98, v108, v109
	v_cvt_pk_bf16_f32 v99, v112, v113
	global_store_dwordx4 v[104:105], v[96:99], off offset:256
	s_and_b64 vcc, exec, s[8:9]
	s_nop 0
	v_or_b32_e32 v96, 32, v146
	v_ashrrev_i32_e32 v97, 31, v96
	v_lshlrev_b64 v[98:99], 7, v[96:97]
	v_lshl_add_u64 v[98:99], s[20:21], 0, v[98:99]
	v_lshl_add_u64 v[102:103], v[144:145], 2, v[98:99]
	s_nop 0
	v_mov_b32_e32 v106, v98
	v_mov_b32_e32 v107, v102
	v_mov_b32_e32 v102, v99
	v_mov_b32_e32 v98, v100
	v_mov_b32_e32 v99, v104
	v_mov_b32_e32 v104, v101
	v_pk_add_f32 v[100:101], v[106:107], v[102:103]
	v_pk_add_f32 v[98:99], v[98:99], v[104:105]
	s_nop 0
	v_pk_add_f32 v[98:99], v[100:101], v[98:99]
	s_nop 0
	v_add_f32_e32 v98, v98, v99
	v_add_f32_e32 v98, v98, v99
	v_add_f32_e32 v98, v98, v99
	v_fmamk_f32 v98, v98, 0x3a000000, v162
	v_mul_f32_e32 v99, 0x4b800000, v98
	v_cmp_gt_f32_e64 s[10:11], s58, v98
	s_nop 1
	v_cndmask_b32_e64 v98, v98, v99, s[10:11]
	s_nop 0
	v_mov_b32_e32 v98, v228
	v_mov_b32_e32 v99, v98
	s_mov_b64 s[10:11], -1
	s_cbranch_vccnz .LBB0_321
	v_mov_b32_e32 v102, v98
	v_mov_b32_e32 v103, v98
	v_pk_mul_f32 v[104:105], v[94:95], v[102:103]
	v_pk_mul_f32 v[100:101], v[92:93], v[98:99]
	v_pk_mul_f32 v[106:107], v[90:91], v[102:103]
	v_pk_mul_f32 v[102:103], v[88:89], v[98:99]
	s_mov_b64 s[10:11], 0

; __device__ __forceinline__ unsigned cvt_pk_bf16(float lo, float hi) { unsigned r; asm volatile("v_cvt_pk_bf16_f32 %0, %1, %2" : "=v"(r) : "v"(lo), "v"(hi)); return r; }
;     __device__ __forceinline__ void operator()(const f32x4 (&acc)[2][2][4][2], const Unit& u, int wr, int wc, int fr, int fq) const {
;     ...
;             for (int m = 0; m < 4; ++m) { const int row = row0 + ai * HALF + m * 16; const float rs = row_rstd(ssq, row, fr, fq);
;                 bf16_t* rowp = base + (size_t)row * ldc + col0;
; #pragma unroll
;                 for (int bj = 0; bj < 2; ++bj) { f32x4 v0, v1;
;                     if (sig) { const float nr = -1.4426950408889634f * rs;
; #pragma unroll
;                         for (int j = 0; j < 4; ++j) { v0[j] = __builtin_amdgcn_rcpf(1.0f + __builtin_amdgcn_exp2f(acc[ai][bj][m][0][j] * nr)); v1[j] = __builtin_amdgcn_rcpf(1.0f + __builtin_amdgcn_exp2f(acc[ai][bj][m][1][j] * nr)); } }
;                     else { v0 = acc[ai][bj][m][0] * rs; v1 = acc[ai][bj][m][1] * rs; }
;                     u32x4 w; w.x = cvt_pk_bf16(v0[0], v0[1]); w.y = cvt_pk_bf16(v0[2], v0[3]); w.z = cvt_pk_bf16(v1[0], v1[1]); w.w = cvt_pk_bf16(v1[2], v1[3]);
;                     *(u32x4*)(rowp + bj * HALF) = w; }
.LBB0_327:
	v_cvt_pk_bf16_f32 v80, v90, v91
	v_cvt_pk_bf16_f32 v81, v94, v95
	v_cvt_pk_bf16_f32 v82, v92, v93
	v_cvt_pk_bf16_f32 v83, v96, v97
	global_store_dwordx4 v[88:89], v[80:83], off offset:256
	s_and_b64 vcc, exec, s[8:9]
	s_nop 0
	v_or_b32_e32 v80, 48, v146
	v_ashrrev_i32_e32 v81, 31, v80
	v_lshlrev_b64 v[82:83], 7, v[80:81]
	v_lshl_add_u64 v[82:83], s[20:21], 0, v[82:83]
	v_lshl_add_u64 v[86:87], v[144:145], 2, v[82:83]
	s_nop 0
	v_mov_b32_e32 v90, v82
	v_mov_b32_e32 v91, v86
	v_mov_b32_e32 v86, v83
	v_mov_b32_e32 v82, v84
	v_mov_b32_e32 v83, v88
	v_mov_b32_e32 v88, v85
	v_pk_add_f32 v[84:85], v[90:91], v[86:87]
	v_pk_add_f32 v[82:83], v[82:83], v[88:89]
	s_nop 0
	v_pk_add_f32 v[82:83], v[84:85], v[82:83]
	s_nop 0
	v_add_f32_e32 v82, v82, v83
	v_add_f32_e32 v82, v82, v83
	v_add_f32_e32 v82, v82, v83
	v_fmamk_f32 v82, v82, 0x3a000000, v162
	v_mul_f32_e32 v83, 0x4b800000, v82
	v_cmp_gt_f32_e64 s[10:11], s58, v82
	s_nop 1
	v_cndmask_b32_e64 v82, v82, v83, s[10:11]
	s_nop 0
	v_mov_b32_e32 v82, v229
	v_mov_b32_e32 v83, v82
	s_mov_b64 s[10:11], -1
	s_cbranch_vccnz .LBB0_329
	v_mov_b32_e32 v86, v82
	v_mov_b32_e32 v87, v82
	v_pk_mul_f32 v[88:89], v[78:79], v[86:87]
	v_pk_mul_f32 v[84:85], v[76:77], v[82:83]
	v_pk_mul_f32 v[90:91], v[74:75], v[86:87]
	v_pk_mul_f32 v[86:87], v[72:73], v[82:83]
	s_mov_b64 s[10:11], 0

; __device__ __forceinline__ unsigned cvt_pk_bf16(float lo, float hi) { unsigned r; asm volatile("v_cvt_pk_bf16_f32 %0, %1, %2" : "=v"(r) : "v"(lo), "v"(hi)); return r; }
;     __device__ __forceinline__ void operator()(const f32x4 (&acc)[2][2][4][2], const Unit& u, int wr, int wc, int fr, int fq) const {
;     ...
;             for (int m = 0; m < 4; ++m) { const int row = row0 + ai * HALF + m * 16; const float rs = row_rstd(ssq, row, fr, fq);
;                 bf16_t* rowp = base + (size_t)row * ldc + col0;
; #pragma unroll
;                 for (int bj = 0; bj < 2; ++bj) { f32x4 v0, v1;
;                     if (sig) { const float nr = -1.4426950408889634f * rs;
; #pragma unroll
;                         for (int j = 0; j < 4; ++j) { v0[j] = __builtin_amdgcn_rcpf(1.0f + __builtin_amdgcn_exp2f(acc[ai][bj][m][0][j] * nr)); v1[j] = __builtin_amdgcn_rcpf(1.0f + __builtin_amdgcn_exp2f(acc[ai][bj][m][1][j] * nr)); } }
;                     else { v0 = acc[ai][bj][m][0] * rs; v1 = acc[ai][bj][m][1] * rs; }
;                     u32x4 w; w.x = cvt_pk_bf16(v0[0], v0[1]); w.y = cvt_pk_bf16(v0[2], v0[3]); w.z = cvt_pk_bf16(v1[0], v1[1]); w.w = cvt_pk_bf16(v1[2], v1[3]);
;                     *(u32x4*)(rowp + bj * HALF) = w; }
.LBB0_335:
	v_cvt_pk_bf16_f32 v64, v74, v75
	v_cvt_pk_bf16_f32 v65, v78, v79
	v_cvt_pk_bf16_f32 v66, v76, v77
	v_cvt_pk_bf16_f32 v67, v80, v81
	global_store_dwordx4 v[72:73], v[64:67], off offset:256
	s_and_b64 vcc, exec, s[8:9]
	s_nop 0
	v_add_u32_e32 v64, 0x80, v146
	v_ashrrev_i32_e32 v65, 31, v64
	v_lshlrev_b64 v[66:67], 7, v[64:65]
	v_lshl_add_u64 v[66:67], s[20:21], 0, v[66:67]
	v_lshl_add_u64 v[70:71], v[144:145], 2, v[66:67]
	s_nop 0
	v_mov_b32_e32 v74, v66
	v_mov_b32_e32 v75, v70
	v_mov_b32_e32 v70, v67
	v_mov_b32_e32 v66, v68
	v_mov_b32_e32 v67, v72
	v_mov_b32_e32 v72, v69
	v_pk_add_f32 v[68:69], v[74:75], v[70:71]
	v_pk_add_f32 v[66:67], v[66:67], v[72:73]
	s_nop 0
	v_pk_add_f32 v[66:67], v[68:69], v[66:67]
	s_nop 0
	v_add_f32_e32 v66, v66, v67
	v_add_f32_e32 v66, v66, v67
	v_add_f32_e32 v66, v66, v67
	v_fmamk_f32 v66, v66, 0x3a000000, v162
	v_mul_f32_e32 v67, 0x4b800000, v66
	v_cmp_gt_f32_e64 s[10:11], s58, v66
	s_nop 1
	v_cndmask_b32_e64 v66, v66, v67, s[10:11]
	s_nop 0
	v_mov_b32_e32 v66, v230
	v_mov_b32_e32 v67, v66
	s_mov_b64 s[10:11], -1
	s_cbranch_vccnz .LBB0_337
	v_mov_b32_e32 v70, v66
	v_mov_b32_e32 v71, v66
	v_pk_mul_f32 v[72:73], v[62:63], v[70:71]
	v_pk_mul_f32 v[68:69], v[60:61], v[66:67]
	v_pk_mul_f32 v[74:75], v[58:59], v[70:71]
	v_pk_mul_f32 v[70:71], v[56:57], v[66:67]
	s_mov_b64 s[10:11], 0

; __device__ __forceinline__ unsigned cvt_pk_bf16(float lo, float hi) { unsigned r; asm volatile("v_cvt_pk_bf16_f32 %0, %1, %2" : "=v"(r) : "v"(lo), "v"(hi)); return r; }
;     __device__ __forceinline__ void operator()(const f32x4 (&acc)[2][2][4][2], const Unit& u, int wr, int wc, int fr, int fq) const {
;     ...
;             for (int m = 0; m < 4; ++m) { const int row = row0 + ai * HALF + m * 16; const float rs = row_rstd(ssq, row, fr, fq);
;                 bf16_t* rowp = base + (size_t)row * ldc + col0;
; #pragma unroll
;                 for (int bj = 0; bj < 2; ++bj) { f32x4 v0, v1;
;                     if (sig) { const float nr = -1.4426950408889634f * rs;
; #pragma unroll
;                         for (int j = 0; j < 4; ++j) { v0[j] = __builtin_amdgcn_rcpf(1.0f + __builtin_amdgcn_exp2f(acc[ai][bj][m][0][j] * nr)); v1[j] = __builtin_amdgcn_rcpf(1.0f + __builtin_amdgcn_exp2f(acc[ai][bj][m][1][j] * nr)); } }
;                     else { v0 = acc[ai][bj][m][0] * rs; v1 = acc[ai][bj][m][1] * rs; }
;                     u32x4 w; w.x = cvt_pk_bf16(v0[0], v0[1]); w.y = cvt_pk_bf16(v0[2], v0[3]); w.z = cvt_pk_bf16(v1[0], v1[1]); w.w = cvt_pk_bf16(v1[2], v1[3]);
;                     *(u32x4*)(rowp + bj * HALF) = w; }
.LBB0_343:
	v_cvt_pk_bf16_f32 v48, v58, v59
	v_cvt_pk_bf16_f32 v49, v62, v63
	v_cvt_pk_bf16_f32 v50, v60, v61
	v_cvt_pk_bf16_f32 v51, v64, v65
	global_store_dwordx4 v[56:57], v[48:51], off offset:256
	s_and_b64 vcc, exec, s[8:9]
	s_nop 0
	v_add_u32_e32 v48, 0x90, v146
	v_ashrrev_i32_e32 v49, 31, v48
	v_lshlrev_b64 v[50:51], 7, v[48:49]
	v_lshl_add_u64 v[50:51], s[20:21], 0, v[50:51]
	v_lshl_add_u64 v[54:55], v[144:145], 2, v[50:51]
	s_nop 0
	v_mov_b32_e32 v58, v50
	v_mov_b32_e32 v59, v54
	v_mov_b32_e32 v54, v51
	v_mov_b32_e32 v50, v52
	v_mov_b32_e32 v51, v56
	v_mov_b32_e32 v56, v53
	v_pk_add_f32 v[52:53], v[58:59], v[54:55]
	v_pk_add_f32 v[50:51], v[50:51], v[56:57]
	s_nop 0
	v_pk_add_f32 v[50:51], v[52:53], v[50:51]
	s_nop 0
	v_add_f32_e32 v50, v50, v51
	v_add_f32_e32 v50, v50, v51
	v_add_f32_e32 v50, v50, v51
	v_fmamk_f32 v50, v50, 0x3a000000, v162
	v_mul_f32_e32 v51, 0x4b800000, v50
	v_cmp_gt_f32_e64 s[10:11], s58, v50
	s_nop 1
	v_cndmask_b32_e64 v50, v50, v51, s[10:11]
	s_nop 0
	v_mov_b32_e32 v50, v231
	v_mov_b32_e32 v51, v50
	s_mov_b64 s[10:11], -1
	s_cbranch_vccnz .LBB0_345
	v_mov_b32_e32 v54, v50
	v_mov_b32_e32 v55, v50
	v_pk_mul_f32 v[56:57], v[46:47], v[54:55]
	v_pk_mul_f32 v[52:53], v[44:45], v[50:51]
	v_pk_mul_f32 v[58:59], v[42:43], v[54:55]
	v_pk_mul_f32 v[54:55], v[40:41], v[50:51]
	s_mov_b64 s[10:11], 0

; __device__ __forceinline__ unsigned cvt_pk_bf16(float lo, float hi) { unsigned r; asm volatile("v_cvt_pk_bf16_f32 %0, %1, %2" : "=v"(r) : "v"(lo), "v"(hi)); return r; }
;     __device__ __forceinline__ void operator()(const f32x4 (&acc)[2][2][4][2], const Unit& u, int wr, int wc, int fr, int fq) const {
;     ...
;             for (int m = 0; m < 4; ++m) { const int row = row0 + ai * HALF + m * 16; const float rs = row_rstd(ssq, row, fr, fq);
;                 bf16_t* rowp = base + (size_t)row * ldc + col0;
; #pragma unroll
;                 for (int bj = 0; bj < 2; ++bj) { f32x4 v0, v1;
;                     if (sig) { const float nr = -1.4426950408889634f * rs;
; #pragma unroll
;                         for (int j = 0; j < 4; ++j) { v0[j] = __builtin_amdgcn_rcpf(1.0f + __builtin_amdgcn_exp2f(acc[ai][bj][m][0][j] * nr)); v1[j] = __builtin_amdgcn_rcpf(1.0f + __builtin_amdgcn_exp2f(acc[ai][bj][m][1][j] * nr)); } }
;                     else { v0 = acc[ai][bj][m][0] * rs; v1 = acc[ai][bj][m][1] * rs; }
;                     u32x4 w; w.x = cvt_pk_bf16(v0[0], v0[1]); w.y = cvt_pk_bf16(v0[2], v0[3]); w.z = cvt_pk_bf16(v1[0], v1[1]); w.w = cvt_pk_bf16(v1[2], v1[3]);
;                     *(u32x4*)(rowp + bj * HALF) = w; }
.LBB0_351:
	v_cvt_pk_bf16_f32 v32, v42, v43
	v_cvt_pk_bf16_f32 v33, v46, v47
	v_cvt_pk_bf16_f32 v34, v44, v45
	v_cvt_pk_bf16_f32 v35, v48, v49
	global_store_dwordx4 v[40:41], v[32:35], off offset:256
	s_and_b64 vcc, exec, s[8:9]
	s_nop 0
	v_add_u32_e32 v32, 0xa0, v146
	v_ashrrev_i32_e32 v33, 31, v32
	v_lshlrev_b64 v[34:35], 7, v[32:33]
	v_lshl_add_u64 v[34:35], s[20:21], 0, v[34:35]
	v_lshl_add_u64 v[38:39], v[144:145], 2, v[34:35]
	s_nop 0
	v_mov_b32_e32 v42, v34
	v_mov_b32_e32 v43, v38
	v_mov_b32_e32 v38, v35
	v_mov_b32_e32 v34, v36
	v_mov_b32_e32 v35, v40
	v_mov_b32_e32 v40, v37
	v_pk_add_f32 v[36:37], v[42:43], v[38:39]
	v_pk_add_f32 v[34:35], v[34:35], v[40:41]
	s_nop 0
	v_pk_add_f32 v[34:35], v[36:37], v[34:35]
	s_nop 0
	v_add_f32_e32 v34, v34, v35
	v_add_f32_e32 v34, v34, v35
	v_add_f32_e32 v34, v34, v35
	v_fmamk_f32 v34, v34, 0x3a000000, v162
	v_mul_f32_e32 v35, 0x4b800000, v34
	v_cmp_gt_f32_e64 s[10:11], s58, v34
	s_nop 1
	v_cndmask_b32_e64 v34, v34, v35, s[10:11]
	s_nop 0
	v_mov_b32_e32 v34, v232
	v_mov_b32_e32 v35, v34
	s_mov_b64 s[10:11], -1
	s_cbranch_vccnz .LBB0_353
	v_mov_b32_e32 v38, v34
	v_mov_b32_e32 v39, v34
	v_pk_mul_f32 v[40:41], v[30:31], v[38:39]
	v_pk_mul_f32 v[36:37], v[28:29], v[34:35]
	v_pk_mul_f32 v[42:43], v[26:27], v[38:39]
	v_pk_mul_f32 v[38:39], v[24:25], v[34:35]
	s_mov_b64 s[10:11], 0

; __device__ __forceinline__ unsigned cvt_pk_bf16(float lo, float hi) { unsigned r; asm volatile("v_cvt_pk_bf16_f32 %0, %1, %2" : "=v"(r) : "v"(lo), "v"(hi)); return r; }
;     __device__ __forceinline__ void operator()(const f32x4 (&acc)[2][2][4][2], const Unit& u, int wr, int wc, int fr, int fq) const {
;     ...
;             for (int m = 0; m < 4; ++m) { const int row = row0 + ai * HALF + m * 16; const float rs = row_rstd(ssq, row, fr, fq);
;                 bf16_t* rowp = base + (size_t)row * ldc + col0;
; #pragma unroll
;                 for (int bj = 0; bj < 2; ++bj) { f32x4 v0, v1;
;                     if (sig) { const float nr = -1.4426950408889634f * rs;
; #pragma unroll
;                         for (int j = 0; j < 4; ++j) { v0[j] = __builtin_amdgcn_rcpf(1.0f + __builtin_amdgcn_exp2f(acc[ai][bj][m][0][j] * nr)); v1[j] = __builtin_amdgcn_rcpf(1.0f + __builtin_amdgcn_exp2f(acc[ai][bj][m][1][j] * nr)); } }
;                     else { v0 = acc[ai][bj][m][0] * rs; v1 = acc[ai][bj][m][1] * rs; }
;                     u32x4 w; w.x = cvt_pk_bf16(v0[0], v0[1]); w.y = cvt_pk_bf16(v0[2], v0[3]); w.z = cvt_pk_bf16(v1[0], v1[1]); w.w = cvt_pk_bf16(v1[2], v1[3]);
;                     *(u32x4*)(rowp + bj * HALF) = w; }
.LBB0_359:
	v_cvt_pk_bf16_f32 v16, v26, v27
	v_cvt_pk_bf16_f32 v17, v30, v31
	v_cvt_pk_bf16_f32 v18, v28, v29
	v_cvt_pk_bf16_f32 v19, v32, v33
	global_store_dwordx4 v[24:25], v[16:19], off offset:256
	s_and_b64 vcc, exec, s[8:9]
	s_nop 0
	v_add_u32_e32 v16, 0xb0, v146
	v_ashrrev_i32_e32 v17, 31, v16
	v_lshlrev_b64 v[18:19], 7, v[16:17]
	v_lshl_add_u64 v[18:19], s[20:21], 0, v[18:19]
	v_lshl_add_u64 v[22:23], v[144:145], 2, v[18:19]
	s_nop 0
	v_mov_b32_e32 v26, v18
	v_mov_b32_e32 v27, v22
	v_mov_b32_e32 v22, v19
	v_mov_b32_e32 v18, v20
	v_mov_b32_e32 v19, v24
	v_mov_b32_e32 v24, v21
	v_pk_add_f32 v[20:21], v[26:27], v[22:23]
	v_pk_add_f32 v[18:19], v[18:19], v[24:25]
	s_nop 0
	v_pk_add_f32 v[18:19], v[20:21], v[18:19]
	s_nop 0
	v_add_f32_e32 v18, v18, v19
	v_add_f32_e32 v18, v18, v19
	v_add_f32_e32 v18, v18, v19
	v_fmamk_f32 v18, v18, 0x3a000000, v162
	v_mul_f32_e32 v19, 0x4b800000, v18
	v_cmp_gt_f32_e64 s[10:11], s58, v18
	s_nop 1
	v_cndmask_b32_e64 v18, v18, v19, s[10:11]
	s_nop 0
	v_mov_b32_e32 v18, v233
	v_mov_b32_e32 v19, v18
	s_mov_b64 s[10:11], -1
	s_cbranch_vccnz .LBB0_361
	v_mov_b32_e32 v22, v18
	v_mov_b32_e32 v23, v18
	v_pk_mul_f32 v[24:25], v[14:15], v[22:23]
	v_pk_mul_f32 v[20:21], v[12:13], v[18:19]
	v_pk_mul_f32 v[26:27], v[10:11], v[22:23]
	v_pk_mul_f32 v[22:23], v[8:9], v[18:19]
	s_mov_b64 s[10:11], 0

;     __device__ bool next(int i, Unit& u) const { if (!StaticOrder::next(i, u)) return false; u.aoff = (u.pn >> 1) * 512; return true; }
;     __host__ __device__ bool next(int i, Unit& u) const {
;         const long L = (long)i * G + c; if (L >= nwg) return false;
;         int wgid = (int)L; { const int q = nwg / NXCD, r = nwg % NXCD, xcd = wgid % NXCD, off = wgid / NXCD; wgid = (xcd < r ? xcd * (q + 1) : r * (q + 1) + (xcd - r) * q) + off; }
;         const int nig = WGM * nN, gid = wgid / nig, fm = gid * WGM, gsz = (nM - fm) < WGM ? (nM - fm) : WGM;
;         u.pm = fm + ((wgid % nig) % gsz); u.pn = (wgid % nig) / gsz; u.aoff = 0; return true;
; template <class Epi, class Sched, bool ALIGN_EPI = false, bool SP2 = false>
; __device__ __forceinline__ void gemm_phase(PG8_LAS unsigned char* lds, const Gemm g, const Sched& S, const Epi& E) {
;     ...
;     Unit cur, nxt; int ui = 0;
;     if (!S.next(0, cur)) return;
.LBB0_877:
	s_or_b64 exec, exec, s[54:55]
	s_cmpk_lt_i32 s2, 0x400
	s_cselect_b64 s[54:55], -1, 0
	s_mov_b64 s[8:9], s[92:93]
	v_mov_b32_e32 v8, v167
	s_and_b64 vcc, exec, s[54:55]
	s_waitcnt lgkmcnt(0)
	s_barrier
	s_mov_b32 s98, -1
	s_cbranch_vccz .LBB0_879
	s_lshr_b32 s0, s80, 29
	s_add_i32 s0, s2, s0
	s_and_b32 s1, s0, -8
	s_sub_i32 s1, s2, s1
	s_lshl_b32 s4, s1, 7
	s_ashr_i32 s0, s0, 3
	s_mul_i32 s3, s1, 0x81
	s_cmp_lt_i32 s1, 0
	s_cselect_b32 s1, s3, s4
	s_add_i32 s0, s1, s0
	s_ashr_i32 s1, s0, 31
	s_lshr_b32 s1, s1, 25
	s_add_i32 s1, s0, s1
	s_ashr_i32 s3, s1, 7
	s_and_b32 s1, s1, 0xffffff80
	s_sub_i32 s0, s0, s1
	s_bfe_i32 s1, s0, 0x80000
	s_bfe_u32 s1, s1, 0x3000c
	s_add_i32 s1, s0, s1
	s_bfe_i32 s4, s1, 0x80000
	s_and_b32 s1, s1, 0xf8
	s_sub_i32 s0, s0, s1
	s_lshl_b32 s3, s3, 3
	s_sext_i32_i16 s4, s4
	s_sext_i32_i8 s0, s0
	s_add_i32 s12, s3, s0
	s_ashr_i32 s10, s4, 3

; #define PG8_STAGE(bufoff, gbase, voff) do { _Pragma("unroll") for (int _i = 0; _i < 2; ++_i) \
;         __builtin_amdgcn_global_load_lds((const unsigned*)((const char*)(gbase) + (voff)[_i]), (PG8_LAS unsigned*)(lds + (bufoff) + ldsw + _i * 8192), 16, 0, 0); } while (0)
; #define PG8_LDA(dst, b, h) do { _Pragma("unroll") for (int m = 0; m < 4; ++m) _Pragma("unroll") for (int k = 0; k < 2; ++k) dst[m][k] = *(const PG8_LAS bf16x8*)(lds + PG8_SA(b, h) + aoff + m * 2048 + k * 1024); } while (0)
; #define PG8_LDB(dst, b, h) do { _Pragma("unroll") for (int n = 0; n < 2; ++n) _Pragma("unroll") for (int k = 0; k < 2; ++k) dst[n][k] = *(const PG8_LAS bf16x8*)(lds + PG8_SB(b, h) + boff + n * 2048 + k * 1024); } while (0)
; #define PG8_SCHED __builtin_amdgcn_sched_barrier(0)
;     __device__ bool next(int i, Unit& u) const { if (!StaticOrder::next(i, u)) return false; u.aoff = (u.pn >> 1) * 512; return true; }
; template <class Epi, class Sched, bool ALIGN_EPI = false, bool SP2 = false>
; __device__ __forceinline__ void gemm_phase(PG8_LAS unsigned char* lds, const Gemm g, const Sched& S, const Epi& E) {
;     ...
;         const bool has_next = S.next(ui + 1, nxt);
;         const char* nA = has_next ? (const char*)g.A + (size_t)nxt.pm * tstepA + nxt.aoff : cA; const char* nB = has_next ? (const char*)g.Bt + (size_t)nxt.pn * tstepB : cB;
;         for (int t = 0; t < nt; t += 2) {
;             const bool last = (t == nt - 2);
;             const char* a1 = cA + (size_t)(t + 1) * kstep;
;             const char* a2 = last ? nA : cA + (size_t)(t + 2) * kstep; const char* b2 = last ? nB : cB + (size_t)(t + 2) * kstep;
;             const char* a3 = a2 + kstep; const char* b3 = b2 + kstep;
;             if (last && has_next) S.a_ready(nxt);
;             if constexpr (SP2) {
;             PG8_LDB(B0, 0, 0); PG8_LDB(B1, 0, 1); PG8_SCHED; PG8_LDA(At, 0, 0); PG8_STAGE(PG8_SA(1, 1), a1 + hstepA, voffA);
;     ...
; #pragma unroll
;         for (int a = 0; a < 2; ++a)
; #pragma unroll
;             for (int b = 0; b < 2; ++b)
; #pragma unroll
;                 for (int m = 0; m < 4; ++m)
; #pragma unroll
;                     for (int n = 0; n < 2; ++n) acc[a][b][m][n] = (f32x4){0.f, 0.f, 0.f, 0.f};
;         cur = nxt; cA = nA; cB = nB; ++ui;
.LBB0_891:
	s_ashr_i32 s23, s22, 31
	s_lshl_b64 s[4:5], s[22:23], 20
	s_add_u32 s26, s0, s4
	s_addc_u32 s27, s1, s5
	s_and_b64 s[4:5], s[8:9], exec
	s_cselect_b32 s11, s27, s31
	s_cselect_b32 s13, s26, s30
	s_ashr_i32 s21, s20, 31
	s_lshl_b64 s[4:5], s[20:21], 20
	s_add_u32 s28, s3, s4
	s_addc_u32 s29, s24, s5
	s_and_b64 s[4:5], s[8:9], exec
	s_cselect_b32 s21, s29, s35
	s_cselect_b32 s23, s28, s34
	s_add_u32 s30, s30, 0x80080
	s_addc_u32 s31, s31, 0
	s_add_u32 s59, s34, 0x100
	v_mov_b32_e32 v0, 0
	s_addc_u32 s60, s35, 0
	s_mov_b32 s61, -2
	v_mov_b32_e32 v1, v0
	v_mov_b32_e32 v2, v0
	v_mov_b32_e32 v3, v0
	v_mov_b32_e32 v4, v0
	v_mov_b32_e32 v5, v0
	v_mov_b32_e32 v6, v0
	v_mov_b32_e32 v7, v0
	v_mov_b32_e32 v16, v0
	v_mov_b32_e32 v17, v0
	v_mov_b32_e32 v18, v0
	v_mov_b32_e32 v19, v0
	v_mov_b32_e32 v20, v0
	v_mov_b32_e32 v21, v0
	v_mov_b32_e32 v22, v0
	v_mov_b32_e32 v23, v0
	v_mov_b32_e32 v32, v0
	v_mov_b32_e32 v33, v0
	v_mov_b32_e32 v34, v0
	v_mov_b32_e32 v35, v0
	v_mov_b32_e32 v36, v0
	v_mov_b32_e32 v37, v0
	v_mov_b32_e32 v38, v0
	v_mov_b32_e32 v39, v0
	v_mov_b32_e32 v48, v0
	v_mov_b32_e32 v49, v0
	v_mov_b32_e32 v50, v0
	v_mov_b32_e32 v51, v0
	v_mov_b32_e32 v52, v0
	v_mov_b32_e32 v53, v0
	v_mov_b32_e32 v54, v0
	v_mov_b32_e32 v55, v0
	v_mov_b32_e32 v8, v0
	v_mov_b32_e32 v9, v0
	v_mov_b32_e32 v10, v0
	v_mov_b32_e32 v11, v0
	v_mov_b32_e32 v12, v0
	v_mov_b32_e32 v13, v0
	v_mov_b32_e32 v14, v0
	v_mov_b32_e32 v15, v0
	v_mov_b32_e32 v24, v0
	v_mov_b32_e32 v25, v0
	v_mov_b32_e32 v26, v0
	v_mov_b32_e32 v27, v0
	v_mov_b32_e32 v28, v0
	v_mov_b32_e32 v29, v0
	v_mov_b32_e32 v30, v0
	v_mov_b32_e32 v31, v0
	v_mov_b32_e32 v40, v0
	v_mov_b32_e32 v41, v0
	v_mov_b32_e32 v42, v0
	v_mov_b32_e32 v43, v0
	v_mov_b32_e32 v44, v0
	v_mov_b32_e32 v45, v0
	v_mov_b32_e32 v46, v0
	v_mov_b32_e32 v47, v0
	v_mov_b32_e32 v56, v0
	v_mov_b32_e32 v57, v0
	v_mov_b32_e32 v58, v0
	v_mov_b32_e32 v59, v0
	v_mov_b32_e32 v60, v0
	v_mov_b32_e32 v61, v0
	v_mov_b32_e32 v62, v0
	v_mov_b32_e32 v63, v0
	v_mov_b32_e32 v64, v0
	v_mov_b32_e32 v65, v0
	v_mov_b32_e32 v66, v0
	v_mov_b32_e32 v67, v0
	v_mov_b32_e32 v68, v0
	v_mov_b32_e32 v69, v0
	v_mov_b32_e32 v70, v0
	v_mov_b32_e32 v71, v0
	v_mov_b32_e32 v80, v0
	v_mov_b32_e32 v81, v0
	v_mov_b32_e32 v82, v0
	v_mov_b32_e32 v83, v0
	v_mov_b32_e32 v84, v0
	v_mov_b32_e32 v85, v0
	v_mov_b32_e32 v86, v0
	v_mov_b32_e32 v87, v0
	v_mov_b32_e32 v96, v0
	v_mov_b32_e32 v97, v0
	v_mov_b32_e32 v98, v0
	v_mov_b32_e32 v99, v0
	v_mov_b32_e32 v100, v0
	v_mov_b32_e32 v101, v0
	v_mov_b32_e32 v102, v0
	v_mov_b32_e32 v103, v0
	v_mov_b32_e32 v112, v0
	v_mov_b32_e32 v113, v0
	v_mov_b32_e32 v114, v0
	v_mov_b32_e32 v115, v0
	v_mov_b32_e32 v116, v0
	v_mov_b32_e32 v117, v0
	v_mov_b32_e32 v118, v0
	v_mov_b32_e32 v119, v0
	v_mov_b32_e32 v72, v0
	v_mov_b32_e32 v73, v0
	v_mov_b32_e32 v74, v0
	v_mov_b32_e32 v75, v0
	v_mov_b32_e32 v76, v0
	v_mov_b32_e32 v77, v0
	v_mov_b32_e32 v78, v0
	v_mov_b32_e32 v79, v0
	v_mov_b32_e32 v88, v0
	v_mov_b32_e32 v89, v0
	v_mov_b32_e32 v90, v0
	v_mov_b32_e32 v91, v0
	v_mov_b32_e32 v92, v0
	v_mov_b32_e32 v93, v0
	v_mov_b32_e32 v94, v0
	v_mov_b32_e32 v95, v0
	v_mov_b32_e32 v104, v0
	v_mov_b32_e32 v105, v0
	v_mov_b32_e32 v106, v0
	v_mov_b32_e32 v107, v0
	v_mov_b32_e32 v108, v0
	v_mov_b32_e32 v109, v0
	v_mov_b32_e32 v110, v0
	v_mov_b32_e32 v111, v0
	v_mov_b32_e32 v120, v0
	v_mov_b32_e32 v121, v0
	v_mov_b32_e32 v122, v0
	v_mov_b32_e32 v123, v0
	v_mov_b32_e32 v124, v0
	v_mov_b32_e32 v125, v0
	v_mov_b32_e32 v126, v0
	v_mov_b32_e32 v127, v0
.LBB0_892:
	ds_read_b128 v[144:147], v155
	ds_read_b128 v[148:151], v155 offset:1024
	ds_read_b128 v[160:163], v155 offset:2048
	ds_read_b128 v[168:171], v155 offset:3072
	ds_read_b128 v[172:175], v156
	ds_read_b128 v[176:179], v156 offset:1024
	ds_read_b128 v[180:183], v156 offset:2048
	ds_read_b128 v[184:187], v156 offset:3072
	s_add_u32 s4, s30, 0xfff80080
	s_addc_u32 s5, s31, -1
	s_cmp_eq_u32 s61, 28
	s_cselect_b32 s37, s11, s5
	s_cselect_b32 s36, s13, s4
	s_cselect_b32 s35, s21, s60
	s_cselect_b32 s34, s23, s59
	v_lshl_add_u64 v[152:153], s[30:31], 0, v[136:137]
	s_add_i32 m0, s25, 0xc000
	ds_read_b128 v[188:191], v157
	ds_read_b128 v[192:195], v157 offset:1024
	ds_read_b128 v[196:199], v157 offset:2048
	ds_read_b128 v[200:203], v157 offset:3072
	ds_read_b128 v[204:207], v157 offset:4096
	ds_read_b128 v[208:211], v157 offset:5120
	ds_read_b128 v[212:215], v157 offset:6144
	ds_read_b128 v[216:219], v157 offset:7168
	global_load_lds_dwordx4 v[152:153], off
	v_lshl_add_u64 v[152:153], s[30:31], 0, v[138:139]
	s_add_i32 m0, s25, 0xe000
	s_nop 0
	global_load_lds_dwordx4 v[152:153], off
	s_waitcnt vmcnt(8)
	s_waitcnt lgkmcnt(0)
	s_barrier
; #define PG8_STAGE(bufoff, gbase, voff) do { _Pragma("unroll") for (int _i = 0; _i < 2; ++_i) \
;         __builtin_amdgcn_global_load_lds((const unsigned*)((const char*)(gbase) + (voff)[_i]), (PG8_LAS unsigned*)(lds + (bufoff) + ldsw + _i * 8192), 16, 0, 0); } while (0)
; #define PG8_LDA(dst, b, h) do { _Pragma("unroll") for (int m = 0; m < 4; ++m) _Pragma("unroll") for (int k = 0; k < 2; ++k) dst[m][k] = *(const PG8_LAS bf16x8*)(lds + PG8_SA(b, h) + aoff + m * 2048 + k * 1024); } while (0)
; #define PG8_LDB(dst, b, h) do { _Pragma("unroll") for (int n = 0; n < 2; ++n) _Pragma("unroll") for (int k = 0; k < 2; ++k) dst[n][k] = *(const PG8_LAS bf16x8*)(lds + PG8_SB(b, h) + boff + n * 2048 + k * 1024); } while (0)
; #define PG8_MMA(ai, bj, At, Bt) do { __builtin_amdgcn_s_setprio(1); _Pragma("unroll") for (int m = 0; m < 4; ++m) _Pragma("unroll") for (int n = 0; n < 2; ++n) _Pragma("unroll") for (int k = 0; k < 2; ++k) \
;         acc[ai][bj][m][n] = __builtin_amdgcn_mfma_f32_16x16x32_bf16(Bt[n][k], At[m][k], acc[ai][bj][m][n], 0, 0, 0); __builtin_amdgcn_s_setprio(0); } while (0)
; #define PG8_WAIT_V(n) asm volatile("s_waitcnt vmcnt(" #n ")" ::: "memory")
; #define PG8_WAIT_L(n) asm volatile("s_waitcnt lgkmcnt(" #n ")" ::: "memory")
; #define PG8_BAR __builtin_amdgcn_s_barrier()
; #define PG8_SCHED __builtin_amdgcn_sched_barrier(0)
; template <class Epi, class Sched, bool ALIGN_EPI = false, bool SP2 = false>
; __device__ __forceinline__ void gemm_phase(PG8_LAS unsigned char* lds, const Gemm g, const Sched& S, const Epi& E) {
;     ...
;             PG8_LDB(B0, 0, 0); PG8_LDB(B1, 0, 1); PG8_SCHED; PG8_LDA(At, 0, 0); PG8_STAGE(PG8_SA(1, 1), a1 + hstepA, voffA);
;             PG8_WAIT_V(8); PG8_WAIT_L(0); PG8_BAR; PG8_MMA(0, 0, At, B0); PG8_MMA(0, 1, At, B1); PG8_BAR; PG8_SCHED;
;             PG8_LDA(At, 0, 1); PG8_STAGE(PG8_SB(0, 0), b2, voffB); PG8_STAGE(PG8_SB(0, 1), b2 + hstepB, voffB); PG8_STAGE(PG8_SA(0, 0), a2, voffA);
;             PG8_WAIT_V(8); PG8_WAIT_L(0); PG8_BAR; PG8_MMA(1, 0, At, B0); PG8_MMA(1, 1, At, B1); PG8_BAR; PG8_SCHED;
	s_setprio 1
	s_waitcnt lgkmcnt(0)
	v_mfma_f32_16x16x32_bf16 v[124:127], v[144:147], v[188:191], v[124:127]
	v_mfma_f32_16x16x32_bf16 v[120:123], v[160:163], v[188:191], v[120:123]
	v_mfma_f32_16x16x32_bf16 v[108:111], v[144:147], v[196:199], v[108:111]
	v_mfma_f32_16x16x32_bf16 v[104:107], v[160:163], v[196:199], v[104:107]
	v_mfma_f32_16x16x32_bf16 v[92:95], v[144:147], v[204:207], v[92:95]
	v_mfma_f32_16x16x32_bf16 v[88:91], v[160:163], v[204:207], v[88:91]
	v_mfma_f32_16x16x32_bf16 v[76:79], v[144:147], v[212:215], v[76:79]
	v_mfma_f32_16x16x32_bf16 v[72:75], v[160:163], v[212:215], v[72:75]
	v_mfma_f32_16x16x32_bf16 v[124:127], v[148:151], v[192:195], v[124:127]
	v_mfma_f32_16x16x32_bf16 v[120:123], v[168:171], v[192:195], v[120:123]
	v_mfma_f32_16x16x32_bf16 v[108:111], v[148:151], v[200:203], v[108:111]
	v_mfma_f32_16x16x32_bf16 v[104:107], v[168:171], v[200:203], v[104:107]
	v_mfma_f32_16x16x32_bf16 v[92:95], v[148:151], v[208:211], v[92:95]
	v_mfma_f32_16x16x32_bf16 v[88:91], v[168:171], v[208:211], v[88:91]
	v_mfma_f32_16x16x32_bf16 v[76:79], v[148:151], v[216:219], v[76:79]
	v_mfma_f32_16x16x32_bf16 v[72:75], v[168:171], v[216:219], v[72:75]
	s_setprio 0
	s_setprio 1
	v_mfma_f32_16x16x32_bf16 v[116:119], v[172:175], v[188:191], v[116:119]
	v_mfma_f32_16x16x32_bf16 v[112:115], v[180:183], v[188:191], v[112:115]
	v_mfma_f32_16x16x32_bf16 v[100:103], v[172:175], v[196:199], v[100:103]
	v_mfma_f32_16x16x32_bf16 v[96:99], v[180:183], v[196:199], v[96:99]
	v_mfma_f32_16x16x32_bf16 v[84:87], v[172:175], v[204:207], v[84:87]
	v_mfma_f32_16x16x32_bf16 v[80:83], v[180:183], v[204:207], v[80:83]
	v_mfma_f32_16x16x32_bf16 v[68:71], v[172:175], v[212:215], v[68:71]
	v_mfma_f32_16x16x32_bf16 v[64:67], v[180:183], v[212:215], v[64:67]
	v_mfma_f32_16x16x32_bf16 v[116:119], v[176:179], v[192:195], v[116:119]
	v_mfma_f32_16x16x32_bf16 v[112:115], v[184:187], v[192:195], v[112:115]
	v_mfma_f32_16x16x32_bf16 v[100:103], v[176:179], v[200:203], v[100:103]
	v_mfma_f32_16x16x32_bf16 v[96:99], v[184:187], v[200:203], v[96:99]
	v_mfma_f32_16x16x32_bf16 v[84:87], v[176:179], v[208:211], v[84:87]
	v_mfma_f32_16x16x32_bf16 v[80:83], v[184:187], v[208:211], v[80:83]
	v_mfma_f32_16x16x32_bf16 v[68:71], v[176:179], v[216:219], v[68:71]
	v_mfma_f32_16x16x32_bf16 v[64:67], v[184:187], v[216:219], v[64:67]
	s_setprio 0
	s_barrier
	s_add_i32 s4, s45, s47
	v_lshl_add_u64 v[152:153], s[34:35], 0, v[130:131]
	s_mov_b32 m0, s4
	ds_read_b128 v[188:191], v157 offset:16384
	ds_read_b128 v[192:195], v157 offset:17408
	ds_read_b128 v[196:199], v157 offset:18432
	ds_read_b128 v[200:203], v157 offset:19456
	ds_read_b128 v[204:207], v157 offset:20480
	ds_read_b128 v[208:211], v157 offset:21504
	ds_read_b128 v[212:215], v157 offset:22528
	ds_read_b128 v[216:219], v157 offset:23552
	global_load_lds_dwordx4 v[152:153], off
	s_add_i32 m0, s4, 0x2000
	s_add_u32 s4, s34, 0x80000
	v_lshl_add_u64 v[164:165], s[34:35], 0, v[134:135]
	s_addc_u32 s5, s35, 0
	s_add_i32 s62, s46, s47
	global_load_lds_dwordx4 v[164:165], off
	v_lshl_add_u64 v[220:221], s[4:5], 0, v[130:131]
	s_mov_b32 m0, s62
	v_lshl_add_u64 v[222:223], s[36:37], 0, v[132:133]
	global_load_lds_dwordx4 v[220:221], off
	v_lshl_add_u64 v[220:221], s[4:5], 0, v[134:135]
	s_add_i32 m0, s62, 0x2000
	s_nop 0
	global_load_lds_dwordx4 v[220:221], off
	v_lshl_add_u64 v[220:221], s[36:37], 0, v[128:129]
	s_mov_b32 m0, s25
	s_nop 0
	global_load_lds_dwordx4 v[220:221], off
	s_mov_b32 m0, s33
	s_nop 0
	global_load_lds_dwordx4 v[222:223], off
	s_waitcnt vmcnt(8)
	s_waitcnt lgkmcnt(0)
	s_barrier
	s_setprio 1
	s_waitcnt lgkmcnt(0)
	v_mfma_f32_16x16x32_bf16 v[60:63], v[144:147], v[188:191], v[60:63]
	v_mfma_f32_16x16x32_bf16 v[56:59], v[160:163], v[188:191], v[56:59]
	v_mfma_f32_16x16x32_bf16 v[44:47], v[144:147], v[196:199], v[44:47]
	v_mfma_f32_16x16x32_bf16 v[40:43], v[160:163], v[196:199], v[40:43]
	v_mfma_f32_16x16x32_bf16 v[28:31], v[144:147], v[204:207], v[28:31]
	v_mfma_f32_16x16x32_bf16 v[24:27], v[160:163], v[204:207], v[24:27]
	v_mfma_f32_16x16x32_bf16 v[12:15], v[144:147], v[212:215], v[12:15]
	v_mfma_f32_16x16x32_bf16 v[8:11], v[160:163], v[212:215], v[8:11]
	v_mfma_f32_16x16x32_bf16 v[60:63], v[148:151], v[192:195], v[60:63]
	v_mfma_f32_16x16x32_bf16 v[56:59], v[168:171], v[192:195], v[56:59]
	v_mfma_f32_16x16x32_bf16 v[44:47], v[148:151], v[200:203], v[44:47]
	v_mfma_f32_16x16x32_bf16 v[40:43], v[168:171], v[200:203], v[40:43]
	v_mfma_f32_16x16x32_bf16 v[28:31], v[148:151], v[208:211], v[28:31]
	v_mfma_f32_16x16x32_bf16 v[24:27], v[168:171], v[208:211], v[24:27]
	v_mfma_f32_16x16x32_bf16 v[12:15], v[148:151], v[216:219], v[12:15]
	v_mfma_f32_16x16x32_bf16 v[8:11], v[168:171], v[216:219], v[8:11]
	s_setprio 0
	s_setprio 1
	v_mfma_f32_16x16x32_bf16 v[52:55], v[172:175], v[188:191], v[52:55]
	v_mfma_f32_16x16x32_bf16 v[48:51], v[180:183], v[188:191], v[48:51]
	v_mfma_f32_16x16x32_bf16 v[36:39], v[172:175], v[196:199], v[36:39]
	v_mfma_f32_16x16x32_bf16 v[32:35], v[180:183], v[196:199], v[32:35]
	v_mfma_f32_16x16x32_bf16 v[20:23], v[172:175], v[204:207], v[20:23]
	v_mfma_f32_16x16x32_bf16 v[16:19], v[180:183], v[204:207], v[16:19]
	v_mfma_f32_16x16x32_bf16 v[4:7], v[172:175], v[212:215], v[4:7]
	v_mfma_f32_16x16x32_bf16 v[0:3], v[180:183], v[212:215], v[0:3]
	v_mfma_f32_16x16x32_bf16 v[52:55], v[176:179], v[192:195], v[52:55]
	v_mfma_f32_16x16x32_bf16 v[48:51], v[184:187], v[192:195], v[48:51]
	v_mfma_f32_16x16x32_bf16 v[36:39], v[176:179], v[200:203], v[36:39]
	v_mfma_f32_16x16x32_bf16 v[32:35], v[184:187], v[200:203], v[32:35]
	v_mfma_f32_16x16x32_bf16 v[20:23], v[176:179], v[208:211], v[20:23]
	v_mfma_f32_16x16x32_bf16 v[16:19], v[184:187], v[208:211], v[16:19]
	v_mfma_f32_16x16x32_bf16 v[4:7], v[176:179], v[216:219], v[4:7]
	v_mfma_f32_16x16x32_bf16 v[0:3], v[184:187], v[216:219], v[0:3]
	s_setprio 0
	s_barrier
; #define PG8_STAGE(bufoff, gbase, voff) do { _Pragma("unroll") for (int _i = 0; _i < 2; ++_i) \
;         __builtin_amdgcn_global_load_lds((const unsigned*)((const char*)(gbase) + (voff)[_i]), (PG8_LAS unsigned*)(lds + (bufoff) + ldsw + _i * 8192), 16, 0, 0); } while (0)
; #define PG8_LDA(dst, b, h) do { _Pragma("unroll") for (int m = 0; m < 4; ++m) _Pragma("unroll") for (int k = 0; k < 2; ++k) dst[m][k] = *(const PG8_LAS bf16x8*)(lds + PG8_SA(b, h) + aoff + m * 2048 + k * 1024); } while (0)
; #define PG8_LDB(dst, b, h) do { _Pragma("unroll") for (int n = 0; n < 2; ++n) _Pragma("unroll") for (int k = 0; k < 2; ++k) dst[n][k] = *(const PG8_LAS bf16x8*)(lds + PG8_SB(b, h) + boff + n * 2048 + k * 1024); } while (0)
; #define PG8_MMA(ai, bj, At, Bt) do { __builtin_amdgcn_s_setprio(1); _Pragma("unroll") for (int m = 0; m < 4; ++m) _Pragma("unroll") for (int n = 0; n < 2; ++n) _Pragma("unroll") for (int k = 0; k < 2; ++k) \
;         acc[ai][bj][m][n] = __builtin_amdgcn_mfma_f32_16x16x32_bf16(Bt[n][k], At[m][k], acc[ai][bj][m][n], 0, 0, 0); __builtin_amdgcn_s_setprio(0); } while (0)
; #define PG8_WAIT_V(n) asm volatile("s_waitcnt vmcnt(" #n ")" ::: "memory")
; #define PG8_WAIT_L(n) asm volatile("s_waitcnt lgkmcnt(" #n ")" ::: "memory")
; #define PG8_BAR __builtin_amdgcn_s_barrier()
; #define PG8_SCHED __builtin_amdgcn_sched_barrier(0)
; template <class Epi, class Sched, bool ALIGN_EPI = false, bool SP2 = false>
; __device__ __forceinline__ void gemm_phase(PG8_LAS unsigned char* lds, const Gemm g, const Sched& S, const Epi& E) {
;     ...
;             PG8_LDB(B0, 1, 0); PG8_LDB(B1, 1, 1); PG8_SCHED; PG8_LDA(At, 1, 0); PG8_STAGE(PG8_SA(0, 1), a2 + hstepA, voffA);
;             PG8_WAIT_V(8); PG8_WAIT_L(0); PG8_BAR; PG8_MMA(0, 0, At, B0); PG8_MMA(0, 1, At, B1); PG8_BAR; PG8_SCHED;
;             PG8_LDA(At, 1, 1); PG8_STAGE(PG8_SB(1, 0), b3, voffB); PG8_STAGE(PG8_SB(1, 1), b3 + hstepB, voffB); PG8_STAGE(PG8_SA(1, 0), a3, voffA);
;             PG8_WAIT_V(8); PG8_WAIT_L(0); PG8_BAR; PG8_MMA(1, 0, At, B0); PG8_MMA(1, 1, At, B1); PG8_BAR; PG8_SCHED;
	s_add_i32 s62, 0, 0x18000
	v_add_u32_e32 v166, s62, v154
	s_add_i32 s63, 0, 0x1c000
	ds_read_b128 v[144:147], v166
	ds_read_b128 v[148:151], v166 offset:1024
	ds_read_b128 v[160:163], v166 offset:2048
	ds_read_b128 v[168:171], v166 offset:3072
	v_add_u32_e32 v166, s63, v154
	ds_read_b128 v[172:175], v166
	ds_read_b128 v[176:179], v166 offset:1024
	ds_read_b128 v[180:183], v166 offset:2048
	ds_read_b128 v[184:187], v166 offset:3072
	s_add_u32 s4, s36, 0x80000
	s_addc_u32 s5, s37, 0
	s_mov_b32 m0, s38
	v_lshl_add_u64 v[224:225], s[4:5], 0, v[128:129]
	ds_read_b128 v[188:191], v157 offset:32768
	ds_read_b128 v[192:195], v157 offset:33792
	ds_read_b128 v[196:199], v157 offset:34816
	ds_read_b128 v[200:203], v157 offset:35840
	ds_read_b128 v[204:207], v157 offset:36864
	ds_read_b128 v[208:211], v157 offset:37888
	ds_read_b128 v[212:215], v157 offset:38912
	ds_read_b128 v[216:219], v157 offset:39936
	global_load_lds_dwordx4 v[224:225], off
	v_lshl_add_u64 v[224:225], s[4:5], 0, v[132:133]
	s_mov_b32 m0, s39
	s_nop 0
	global_load_lds_dwordx4 v[224:225], off
	s_waitcnt vmcnt(8)
	s_waitcnt lgkmcnt(0)
	s_barrier
	s_setprio 1
	s_waitcnt lgkmcnt(0)
	v_mfma_f32_16x16x32_bf16 v[124:127], v[144:147], v[188:191], v[124:127]
	v_mfma_f32_16x16x32_bf16 v[120:123], v[160:163], v[188:191], v[120:123]
	v_mfma_f32_16x16x32_bf16 v[108:111], v[144:147], v[196:199], v[108:111]
	v_mfma_f32_16x16x32_bf16 v[104:107], v[160:163], v[196:199], v[104:107]
	v_mfma_f32_16x16x32_bf16 v[92:95], v[144:147], v[204:207], v[92:95]
	v_mfma_f32_16x16x32_bf16 v[88:91], v[160:163], v[204:207], v[88:91]
	v_mfma_f32_16x16x32_bf16 v[76:79], v[144:147], v[212:215], v[76:79]
	v_mfma_f32_16x16x32_bf16 v[72:75], v[160:163], v[212:215], v[72:75]
	v_mfma_f32_16x16x32_bf16 v[124:127], v[148:151], v[192:195], v[124:127]
	v_mfma_f32_16x16x32_bf16 v[120:123], v[168:171], v[192:195], v[120:123]
	v_mfma_f32_16x16x32_bf16 v[108:111], v[148:151], v[200:203], v[108:111]
	v_mfma_f32_16x16x32_bf16 v[104:107], v[168:171], v[200:203], v[104:107]
	v_mfma_f32_16x16x32_bf16 v[92:95], v[148:151], v[208:211], v[92:95]
	v_mfma_f32_16x16x32_bf16 v[88:91], v[168:171], v[208:211], v[88:91]
	v_mfma_f32_16x16x32_bf16 v[76:79], v[148:151], v[216:219], v[76:79]
	v_mfma_f32_16x16x32_bf16 v[72:75], v[168:171], v[216:219], v[72:75]
	s_setprio 0
	s_setprio 1
	v_mfma_f32_16x16x32_bf16 v[116:119], v[172:175], v[188:191], v[116:119]
	v_mfma_f32_16x16x32_bf16 v[112:115], v[180:183], v[188:191], v[112:115]
	v_mfma_f32_16x16x32_bf16 v[100:103], v[172:175], v[196:199], v[100:103]
	v_mfma_f32_16x16x32_bf16 v[96:99], v[180:183], v[196:199], v[96:99]
	v_mfma_f32_16x16x32_bf16 v[84:87], v[172:175], v[204:207], v[84:87]
	v_mfma_f32_16x16x32_bf16 v[80:83], v[180:183], v[204:207], v[80:83]
	v_mfma_f32_16x16x32_bf16 v[68:71], v[172:175], v[212:215], v[68:71]
	v_mfma_f32_16x16x32_bf16 v[64:67], v[180:183], v[212:215], v[64:67]
	v_mfma_f32_16x16x32_bf16 v[116:119], v[176:179], v[192:195], v[116:119]
	v_mfma_f32_16x16x32_bf16 v[112:115], v[184:187], v[192:195], v[112:115]
	v_mfma_f32_16x16x32_bf16 v[100:103], v[176:179], v[200:203], v[100:103]
	v_mfma_f32_16x16x32_bf16 v[96:99], v[184:187], v[200:203], v[96:99]
	v_mfma_f32_16x16x32_bf16 v[84:87], v[176:179], v[208:211], v[84:87]
	v_mfma_f32_16x16x32_bf16 v[80:83], v[184:187], v[208:211], v[80:83]
	v_mfma_f32_16x16x32_bf16 v[68:71], v[176:179], v[216:219], v[68:71]
	v_mfma_f32_16x16x32_bf16 v[64:67], v[184:187], v[216:219], v[64:67]
	s_setprio 0
	s_barrier
	s_add_i32 s4, s62, s47
	v_lshl_add_u64 v[152:153], v[152:153], 0, s[18:19]
	s_mov_b32 m0, s4
	ds_read_b128 v[188:191], v157 offset:49152
	ds_read_b128 v[192:195], v157 offset:50176
	ds_read_b128 v[196:199], v157 offset:51200
	ds_read_b128 v[200:203], v157 offset:52224
	ds_read_b128 v[204:207], v157 offset:53248
	ds_read_b128 v[208:211], v157 offset:54272
	ds_read_b128 v[212:215], v157 offset:55296
	ds_read_b128 v[216:219], v157 offset:56320
	global_load_lds_dwordx4 v[152:153], off
	s_add_i32 m0, s4, 0x2000
	s_add_u32 s4, s34, 0x80080
	v_lshl_add_u64 v[152:153], v[164:165], 0, s[18:19]
	s_addc_u32 s5, s35, 0
	s_add_i32 s34, s63, s47
	global_load_lds_dwordx4 v[152:153], off
	v_lshl_add_u64 v[152:153], s[4:5], 0, v[130:131]
	s_mov_b32 m0, s34
	s_nop 0
	global_load_lds_dwordx4 v[152:153], off
	v_lshl_add_u64 v[152:153], s[4:5], 0, v[134:135]
	s_add_i32 m0, s34, 0x2000
	s_nop 0
	global_load_lds_dwordx4 v[152:153], off
	v_lshl_add_u64 v[152:153], v[220:221], 0, s[18:19]
	s_mov_b32 m0, s41
	s_nop 0
	global_load_lds_dwordx4 v[152:153], off
	v_lshl_add_u64 v[152:153], v[222:223], 0, s[18:19]
	s_mov_b32 m0, s44
	s_nop 0
	global_load_lds_dwordx4 v[152:153], off
	s_waitcnt vmcnt(8)
	s_waitcnt lgkmcnt(0)
	s_barrier
; #define PG8_STAGE(bufoff, gbase, voff) do { _Pragma("unroll") for (int _i = 0; _i < 2; ++_i) \
;         __builtin_amdgcn_global_load_lds((const unsigned*)((const char*)(gbase) + (voff)[_i]), (PG8_LAS unsigned*)(lds + (bufoff) + ldsw + _i * 8192), 16, 0, 0); } while (0)
; template <class Epi, class Sched, bool ALIGN_EPI = false, bool SP2 = false>
; __device__ __forceinline__ void gemm_phase(PG8_LAS unsigned char* lds, const Gemm g, const Sched& S, const Epi& E) {
;     ...
;             PG8_WAIT_V(8); PG8_WAIT_L(0); PG8_BAR; PG8_MMA(1, 0, At, B0); PG8_MMA(1, 1, At, B1); PG8_BAR; PG8_SCHED;
;             } else {
;             PG8_LDB(B0, 0, 0); PG8_SCHED; PG8_LDA(At, 0, 0); PG8_STAGE(PG8_SA(1, 1), a1 + hstepA, voffA);
;             PG8_WAIT_L(8); PG8_BAR; PG8_WAIT_L(0); PG8_MMA(0, 0, At, B0); PG8_BAR; PG8_SCHED;
;             PG8_LDB(B1, 0, 1); PG8_STAGE(PG8_SB(0, 0), b2, voffB);
;             PG8_BAR; PG8_WAIT_L(0); PG8_MMA(0, 1, At, B1); PG8_BAR;
;             PG8_LDA(At, 0, 1); PG8_STAGE(PG8_SA(0, 0), a2, voffA);
;             PG8_BAR; PG8_WAIT_L(0); PG8_MMA(1, 0, At, B0); PG8_BAR; PG8_SCHED;
;             PG8_STAGE(PG8_SB(0, 1), b2 + hstepB, voffB);
;             PG8_WAIT_V(6); PG8_BAR; PG8_MMA(1, 1, At, B1); PG8_BAR;
;             PG8_LDB(B0, 1, 0); PG8_SCHED; PG8_LDA(At, 1, 0); PG8_STAGE(PG8_SA(0, 1), a2 + hstepA, voffA);
;             PG8_WAIT_L(8); PG8_BAR; PG8_WAIT_L(0); PG8_MMA(0, 0, At, B0); PG8_BAR; PG8_SCHED;
;             PG8_LDB(B1, 1, 1); PG8_STAGE(PG8_SB(1, 0), b3, voffB);
;             PG8_BAR; PG8_WAIT_L(0); PG8_MMA(0, 1, At, B1); PG8_BAR;
;             PG8_LDA(At, 1, 1); PG8_STAGE(PG8_SA(1, 0), a3, voffA);
;             PG8_BAR; PG8_WAIT_L(0); PG8_MMA(1, 0, At, B0); PG8_BAR; PG8_SCHED;
;             PG8_STAGE(PG8_SB(1, 1), b3 + hstepB, voffB);
;             PG8_WAIT_V(6); PG8_BAR; PG8_MMA(1, 1, At, B1); PG8_BAR;
;             }
;         }
;         if constexpr (ALIGN_EPI) { if (wr == 0) PG8_BAR; }
; __device__ __forceinline__ float row_rstd(const float* ssqp, int row, int fr, int fq) {
;     const f32x4 p0 = *(const f32x4*)(ssqp + (size_t)row * 32 + fq * 8), p1 = *(const f32x4*)(ssqp + (size_t)row * 32 + fq * 8 + 4);
;     float t = ((p0[0] + p0[1]) + (p0[2] + p0[3])) + ((p1[0] + p1[1]) + (p1[2] + p1[3])); const int ln = fr + 16 * fq;
;     t += shx(t, 16, ln); t += shx(t, 32, ln);
;     return rsqrtf(t * (1.0f / 2048.0f) + RMS_EPS);
; }
	s_setprio 1
	s_waitcnt lgkmcnt(0)
	v_mfma_f32_16x16x32_bf16 v[60:63], v[144:147], v[188:191], v[60:63]
	v_mfma_f32_16x16x32_bf16 v[56:59], v[160:163], v[188:191], v[56:59]
	v_mfma_f32_16x16x32_bf16 v[44:47], v[144:147], v[196:199], v[44:47]
	v_mfma_f32_16x16x32_bf16 v[40:43], v[160:163], v[196:199], v[40:43]
	v_mfma_f32_16x16x32_bf16 v[28:31], v[144:147], v[204:207], v[28:31]
	v_mfma_f32_16x16x32_bf16 v[24:27], v[160:163], v[204:207], v[24:27]
	v_mfma_f32_16x16x32_bf16 v[12:15], v[144:147], v[212:215], v[12:15]
	v_mfma_f32_16x16x32_bf16 v[8:11], v[160:163], v[212:215], v[8:11]
	v_mfma_f32_16x16x32_bf16 v[60:63], v[148:151], v[192:195], v[60:63]
	v_mfma_f32_16x16x32_bf16 v[56:59], v[168:171], v[192:195], v[56:59]
	v_mfma_f32_16x16x32_bf16 v[44:47], v[148:151], v[200:203], v[44:47]
	v_mfma_f32_16x16x32_bf16 v[40:43], v[168:171], v[200:203], v[40:43]
	v_mfma_f32_16x16x32_bf16 v[28:31], v[148:151], v[208:211], v[28:31]
	v_mfma_f32_16x16x32_bf16 v[24:27], v[168:171], v[208:211], v[24:27]
	v_mfma_f32_16x16x32_bf16 v[12:15], v[148:151], v[216:219], v[12:15]
	v_mfma_f32_16x16x32_bf16 v[8:11], v[168:171], v[216:219], v[8:11]
	s_setprio 0
	s_setprio 1
	v_mfma_f32_16x16x32_bf16 v[52:55], v[172:175], v[188:191], v[52:55]
	v_mfma_f32_16x16x32_bf16 v[48:51], v[180:183], v[188:191], v[48:51]
	v_mfma_f32_16x16x32_bf16 v[36:39], v[172:175], v[196:199], v[36:39]
	v_mfma_f32_16x16x32_bf16 v[32:35], v[180:183], v[196:199], v[32:35]
	v_mfma_f32_16x16x32_bf16 v[20:23], v[172:175], v[204:207], v[20:23]
	v_mfma_f32_16x16x32_bf16 v[16:19], v[180:183], v[204:207], v[16:19]
	v_mfma_f32_16x16x32_bf16 v[4:7], v[172:175], v[212:215], v[4:7]
	v_mfma_f32_16x16x32_bf16 v[0:3], v[180:183], v[212:215], v[0:3]
	v_mfma_f32_16x16x32_bf16 v[52:55], v[176:179], v[192:195], v[52:55]
	v_mfma_f32_16x16x32_bf16 v[48:51], v[184:187], v[192:195], v[48:51]
	v_mfma_f32_16x16x32_bf16 v[36:39], v[176:179], v[200:203], v[36:39]
	v_mfma_f32_16x16x32_bf16 v[32:35], v[184:187], v[200:203], v[32:35]
	v_mfma_f32_16x16x32_bf16 v[20:23], v[176:179], v[208:211], v[20:23]
	v_mfma_f32_16x16x32_bf16 v[16:19], v[184:187], v[208:211], v[16:19]
	v_mfma_f32_16x16x32_bf16 v[4:7], v[176:179], v[216:219], v[4:7]
	v_mfma_f32_16x16x32_bf16 v[0:3], v[184:187], v[216:219], v[0:3]
	s_setprio 0
	s_barrier
	s_add_i32 s61, s61, 2
	s_add_u32 s30, s30, 0x100
	s_addc_u32 s31, s31, 0
	s_add_u32 s59, s59, 0x100
	s_addc_u32 s60, s60, 0
	s_cmp_gt_u32 s61, 29
	s_cbranch_scc0 .LBB0_892
	s_and_b64 vcc, exec, s[48:49]
	s_cbranch_vccz .LBB0_895
	s_barrier
.LBB0_895:
	s_cmp_eq_u32 s12, s98
	s_cbranch_scc1 .Lrgin_have
	v_and_b32_e32 v144, 15, v167
	v_lshrrev_b32_e32 v145, 4, v167
	s_lshl_b32 s4, s12, 8
	s_add_i32 s4, s4, s78
	v_or_b32_e32 v146, s4, v144
	v_lshlrev_b32_e32 v147, 7, v146
	v_lshl_add_u32 v147, v145, 5, v147
	v_add_u32_e32 v163, 0x1000, v147
	v_add_u32_e32 v164, 0x4000, v147
	v_add_u32_e32 v165, 0x5000, v147
	global_load_dwordx4 v[168:171], v147, s[16:17]
	global_load_dwordx4 v[172:175], v147, s[16:17] offset:16
	global_load_dwordx4 v[176:179], v147, s[16:17] offset:2048
	global_load_dwordx4 v[180:183], v147, s[16:17] offset:2064
	global_load_dwordx4 v[184:187], v163, s[16:17]
	global_load_dwordx4 v[188:191], v163, s[16:17] offset:16
	global_load_dwordx4 v[192:195], v163, s[16:17] offset:2048
	global_load_dwordx4 v[196:199], v163, s[16:17] offset:2064
	global_load_dwordx4 v[200:203], v164, s[16:17]
	global_load_dwordx4 v[204:207], v164, s[16:17] offset:16
	global_load_dwordx4 v[208:211], v164, s[16:17] offset:2048
	global_load_dwordx4 v[212:215], v164, s[16:17] offset:2064
	global_load_dwordx4 v[216:219], v165, s[16:17]
	global_load_dwordx4 v[220:223], v165, s[16:17] offset:16
	global_load_dwordx4 v[224:227], v165, s[16:17] offset:2048
	global_load_dwordx4 v[228:231], v165, s[16:17] offset:2064
	v_xor_b32_e32 v144, 16, v167
	v_xor_b32_e32 v145, 32, v167
	v_lshlrev_b32_e32 v144, 2, v144
	v_lshlrev_b32_e32 v145, 2, v145
	s_waitcnt vmcnt(0)
	v_add_f32_e32 v168, v168, v169
	v_add_f32_e32 v176, v176, v177
	v_add_f32_e32 v184, v184, v185
	v_add_f32_e32 v192, v192, v193
	v_add_f32_e32 v200, v200, v201
	v_add_f32_e32 v208, v208, v209
	v_add_f32_e32 v216, v216, v217
	v_add_f32_e32 v224, v224, v225
	v_add_f32_e32 v170, v170, v171
	v_add_f32_e32 v178, v178, v179
	v_add_f32_e32 v186, v186, v187
	v_add_f32_e32 v194, v194, v195
	v_add_f32_e32 v202, v202, v203
	v_add_f32_e32 v210, v210, v211
	v_add_f32_e32 v218, v218, v219
	v_add_f32_e32 v226, v226, v227
	v_add_f32_e32 v172, v172, v173
	v_add_f32_e32 v180, v180, v181
	v_add_f32_e32 v188, v188, v189
	v_add_f32_e32 v196, v196, v197
	v_add_f32_e32 v204, v204, v205
	v_add_f32_e32 v212, v212, v213
	v_add_f32_e32 v220, v220, v221
	v_add_f32_e32 v228, v228, v229
	v_add_f32_e32 v174, v174, v175
	v_add_f32_e32 v182, v182, v183
	v_add_f32_e32 v190, v190, v191
	v_add_f32_e32 v198, v198, v199
	v_add_f32_e32 v206, v206, v207
	v_add_f32_e32 v214, v214, v215
	v_add_f32_e32 v222, v222, v223
	v_add_f32_e32 v230, v230, v231
	v_add_f32_e32 v168, v168, v170
	v_add_f32_e32 v176, v176, v178
	v_add_f32_e32 v184, v184, v186
	v_add_f32_e32 v192, v192, v194
	v_add_f32_e32 v200, v200, v202
	v_add_f32_e32 v208, v208, v210
	v_add_f32_e32 v216, v216, v218
	v_add_f32_e32 v224, v224, v226
	v_add_f32_e32 v172, v172, v174
	v_add_f32_e32 v180, v180, v182
	v_add_f32_e32 v188, v188, v190
	v_add_f32_e32 v196, v196, v198
	v_add_f32_e32 v204, v204, v206
	v_add_f32_e32 v212, v212, v214
	v_add_f32_e32 v220, v220, v222
	v_add_f32_e32 v228, v228, v230
	v_add_f32_e32 v168, v168, v172
	v_add_f32_e32 v176, v176, v180
	v_add_f32_e32 v184, v184, v188
	v_add_f32_e32 v192, v192, v196
	v_add_f32_e32 v200, v200, v204
	v_add_f32_e32 v208, v208, v212
	v_add_f32_e32 v216, v216, v220
	v_add_f32_e32 v224, v224, v228
	ds_bpermute_b32 v242, v144, v168
	ds_bpermute_b32 v243, v144, v176
	ds_bpermute_b32 v244, v144, v184
	ds_bpermute_b32 v245, v144, v192
	ds_bpermute_b32 v246, v144, v200
	ds_bpermute_b32 v247, v144, v208
	ds_bpermute_b32 v248, v144, v216
	ds_bpermute_b32 v249, v144, v224
	s_waitcnt lgkmcnt(0)
; __device__ __forceinline__ float shx(float v, int mask, int lane) { return __int_as_float(__builtin_amdgcn_ds_bpermute((lane ^ mask) << 2, __float_as_int(v))); }
; __device__ __forceinline__ float gelu_tanh(float x) { const float p = __builtin_fmaf(x * x, -0.10294325f, -2.3022082f); return x * __builtin_amdgcn_rcpf(1.0f + __builtin_amdgcn_exp2f(x * p)); }
; __device__ __forceinline__ float row_rstd(const float* ssqp, int row, int fr, int fq) {
;     const f32x4 p0 = *(const f32x4*)(ssqp + (size_t)row * 32 + fq * 8), p1 = *(const f32x4*)(ssqp + (size_t)row * 32 + fq * 8 + 4);
;     float t = ((p0[0] + p0[1]) + (p0[2] + p0[3])) + ((p1[0] + p1[1]) + (p1[2] + p1[3])); const int ln = fr + 16 * fq;
;     t += shx(t, 16, ln); t += shx(t, 32, ln);
;     return rsqrtf(t * (1.0f / 2048.0f) + RMS_EPS);
; }
;     __device__ __forceinline__ void operator()(const f32x4 (&acc)[2][2][4][2], const Unit& u, int wr, int wc, int fr, int fq) const {
;     ...
;             for (int m = 0; m < 4; ++m) { const int row = row0 + ai * HALF + m * 16; const float rs = row_rstd(ssq, row, fr, fq);
;                 bf16_t* rowp = base + (size_t)row * 2048 + col0;
; #pragma unroll
;                 for (int bj = 0; bj < 2; ++bj) { f32x4 v0 = acc[ai][bj][m][0] * rs, v1 = acc[ai][bj][m][1] * rs;
;                     if (gate) {
; #pragma unroll
;                         for (int j = 0; j < 4; ++j) { v0[j] = gelu_tanh(v0[j]); v1[j] = gelu_tanh(v1[j]); } }
	v_add_f32_e32 v168, v168, v242
	v_add_f32_e32 v176, v176, v243
	v_add_f32_e32 v184, v184, v244
	v_add_f32_e32 v192, v192, v245
	v_add_f32_e32 v200, v200, v246
	v_add_f32_e32 v208, v208, v247
	v_add_f32_e32 v216, v216, v248
	v_add_f32_e32 v224, v224, v249
	ds_bpermute_b32 v242, v145, v168
	ds_bpermute_b32 v243, v145, v176
	ds_bpermute_b32 v244, v145, v184
	ds_bpermute_b32 v245, v145, v192
	ds_bpermute_b32 v246, v145, v200
	ds_bpermute_b32 v247, v145, v208
	ds_bpermute_b32 v248, v145, v216
	ds_bpermute_b32 v249, v145, v224
	s_waitcnt lgkmcnt(0)
	v_add_f32_e32 v168, v168, v242
	v_add_f32_e32 v176, v176, v243
	v_add_f32_e32 v184, v184, v244
	v_add_f32_e32 v192, v192, v245
	v_add_f32_e32 v200, v200, v246
	v_add_f32_e32 v208, v208, v247
	v_add_f32_e32 v216, v216, v248
	v_add_f32_e32 v224, v224, v249
	v_fmamk_f32 v168, v168, 0x3a000000, v158
	v_fmamk_f32 v176, v176, 0x3a000000, v158
	v_fmamk_f32 v184, v184, 0x3a000000, v158
	v_fmamk_f32 v192, v192, 0x3a000000, v158
	v_fmamk_f32 v200, v200, 0x3a000000, v158
	v_fmamk_f32 v208, v208, 0x3a000000, v158
	v_fmamk_f32 v216, v216, 0x3a000000, v158
	v_fmamk_f32 v224, v224, 0x3a000000, v158
	v_rsq_f32_e32 v169, v168
	v_rsq_f32_e32 v177, v176
	v_rsq_f32_e32 v185, v184
	v_rsq_f32_e32 v193, v192
	v_rsq_f32_e32 v201, v200
	v_rsq_f32_e32 v209, v208
	v_rsq_f32_e32 v217, v216
	v_rsq_f32_e32 v225, v224
	v_mov_b32_e32 v226, v169
	v_mov_b32_e32 v227, v177
	v_mov_b32_e32 v228, v185
	v_mov_b32_e32 v229, v193
	v_mov_b32_e32 v230, v201
	v_mov_b32_e32 v231, v209
	v_mov_b32_e32 v232, v217
	v_mov_b32_e32 v233, v225
	s_mov_b32 s98, s12
.Lrgin_have:
	v_mov_b32_e32 v144, v167
	s_lshl_b32 s4, s12, 8
	s_add_i32 s4, s4, s78
	v_and_b32_e32 v160, 15, v144
	v_or_b32_e32 v146, s4, v160
	v_ashrrev_i32_e32 v161, 4, v144
	v_ashrrev_i32_e32 v147, 31, v146
	v_lshlrev_b32_e32 v144, 3, v161
	v_lshlrev_b64 v[148:149], 7, v[146:147]
	v_ashrrev_i32_e32 v145, 31, v144
	v_lshl_add_u64 v[148:149], s[16:17], 0, v[148:149]
	v_lshl_add_u64 v[152:153], v[144:145], 2, v[148:149]
	v_lshlrev_b32_e32 v161, 6, v161
	v_lshlrev_b32_e32 v166, 2, v160
	v_bitop3_b32 v160, v161, 64, v166 bitop3:0x36
	v_bitop3_b32 v161, v161, s56, v166 bitop3:0x36
	s_cmp_lt_i32 s10, 8
	s_cselect_b64 s[12:13], -1, 0
	s_cmp_gt_i32 s10, 7
	v_mov_b32_e32 v152, v148
	v_mov_b32_e32 v153, v162
	v_mov_b32_e32 v162, v149
	v_mov_b32_e32 v148, v150
	v_mov_b32_e32 v149, v164
	v_mov_b32_e32 v164, v151
	v_pk_add_f32 v[150:151], v[152:153], v[162:163]
	v_pk_add_f32 v[148:149], v[148:149], v[164:165]
	s_nop 0
	v_pk_add_f32 v[148:149], v[150:151], v[148:149]
	s_nop 0
	v_add_f32_e32 v148, v148, v149
	v_add_f32_e32 v148, v148, v149
	v_add_f32_e32 v148, v148, v149
	v_fmamk_f32 v148, v148, 0x3a000000, v158
	v_mul_f32_e32 v149, 0x4b800000, v148
	v_cmp_gt_f32_e32 vcc, s57, v148
	s_nop 1
	v_cndmask_b32_e32 v148, v148, v149, vcc
	s_nop 0
	v_mov_b32_e32 v148, v226
	v_pk_mul_f32 v[126:127], v[126:127], v[148:149] op_sel_hi:[1,0]
	v_pk_mul_f32 v[150:151], v[124:125], v[148:149] op_sel_hi:[1,0]
	v_pk_mul_f32 v[124:125], v[122:123], v[148:149] op_sel_hi:[1,0]
	v_pk_mul_f32 v[152:153], v[120:121], v[148:149] op_sel_hi:[1,0]
	s_cbranch_scc1 .LBB0_897
	v_mul_f32_e32 v149, v126, v126
	v_mul_f32_e32 v121, v152, v152
	v_fmamk_f32 v149, v149, 0xbdd2d3e9, v159
	v_mul_f32_e32 v162, v124, v124
	v_fmamk_f32 v121, v121, 0xbdd2d3e9, v159
	v_mul_f32_e32 v122, v151, v151
	v_mul_f32_e32 v149, v126, v149
	v_fmamk_f32 v162, v162, 0xbdd2d3e9, v159
	v_mul_f32_e32 v121, v152, v121
	v_fmamk_f32 v122, v122, 0xbdd2d3e9, v159
	v_exp_f32_e32 v149, v149
	v_mul_f32_e32 v162, v124, v162
	v_exp_f32_e32 v121, v121
	v_mul_f32_e32 v122, v151, v122
	v_exp_f32_e32 v163, v162
	v_exp_f32_e32 v123, v122
	v_add_f32_e32 v149, 1.0, v149
	v_add_f32_e32 v121, 1.0, v121
	v_rcp_f32_e32 v162, v149
	v_add_f32_e32 v149, 1.0, v163
	v_mul_f32_e32 v163, v127, v127
	v_mul_f32_e32 v120, v150, v150
	v_rcp_f32_e32 v122, v121
	v_add_f32_e32 v121, 1.0, v123
	v_mul_f32_e32 v123, v153, v153
	v_fmamk_f32 v163, v163, 0xbdd2d3e9, v159
	v_mul_f32_e32 v164, v125, v125
	v_fmamk_f32 v120, v120, 0xbdd2d3e9, v159
	v_fmamk_f32 v123, v123, 0xbdd2d3e9, v159
	v_mul_f32_e32 v163, v127, v163
	v_fmamk_f32 v164, v164, 0xbdd2d3e9, v159
	v_mul_f32_e32 v120, v150, v120
	v_mul_f32_e32 v123, v153, v123
	v_exp_f32_e32 v163, v163
	v_mul_f32_e32 v164, v125, v164
	v_exp_f32_e32 v120, v120
	v_exp_f32_e32 v123, v123
	v_exp_f32_e32 v165, v164
	v_rcp_f32_e32 v164, v149
	v_add_f32_e32 v149, 1.0, v163
	v_add_f32_e32 v120, 1.0, v120
	v_add_f32_e32 v123, 1.0, v123
	v_rcp_f32_e32 v163, v149
	v_add_f32_e32 v149, 1.0, v165
	v_rcp_f32_e32 v120, v120
	v_rcp_f32_e32 v121, v121
	v_rcp_f32_e32 v165, v149
	v_rcp_f32_e32 v123, v123
	v_pk_mul_f32 v[126:127], v[126:127], v[162:163]
	v_pk_mul_f32 v[150:151], v[150:151], v[120:121]
	v_pk_mul_f32 v[124:125], v[124:125], v[164:165]
	v_pk_mul_f32 v[152:153], v[152:153], v[122:123]

; __device__ __forceinline__ unsigned cvt_pk_bf16(float lo, float hi) { unsigned r; asm volatile("v_cvt_pk_bf16_f32 %0, %1, %2" : "=v"(r) : "v"(lo), "v"(hi)); return r; }
; __device__ __forceinline__ float gelu_tanh(float x) { const float p = __builtin_fmaf(x * x, -0.10294325f, -2.3022082f); return x * __builtin_amdgcn_rcpf(1.0f + __builtin_amdgcn_exp2f(x * p)); }
;     __device__ __forceinline__ void operator()(const f32x4 (&acc)[2][2][4][2], const Unit& u, int wr, int wc, int fr, int fq) const {
;     ...
;             for (int m = 0; m < 4; ++m) { const int row = row0 + ai * HALF + m * 16; const float rs = row_rstd(ssq, row, fr, fq);
;                 bf16_t* rowp = base + (size_t)row * 2048 + col0;
; #pragma unroll
;                 for (int bj = 0; bj < 2; ++bj) { f32x4 v0 = acc[ai][bj][m][0] * rs, v1 = acc[ai][bj][m][1] * rs;
;                     if (gate) {
; #pragma unroll
;                         for (int j = 0; j < 4; ++j) { v0[j] = gelu_tanh(v0[j]); v1[j] = gelu_tanh(v1[j]); } }
;                     u32x4 w; w.x = cvt_pk_bf16(v0[0], v0[1]); w.y = cvt_pk_bf16(v0[2], v0[3]); w.z = cvt_pk_bf16(v1[0], v1[1]); w.w = cvt_pk_bf16(v1[2], v1[3]);
;                     *(u32x4*)(rowp + bj * HALF) = w; }
.LBB0_899:
	v_cvt_pk_bf16_f32 v116, v116, v117
	v_cvt_pk_bf16_f32 v117, v118, v119
	s_nop 0
	v_cvt_pk_bf16_f32 v118, v112, v113
	v_or_b32_e32 v112, 16, v146
	v_ashrrev_i32_e32 v113, 31, v112
	v_cvt_pk_bf16_f32 v119, v114, v115
	v_lshlrev_b64 v[114:115], 7, v[112:113]
	global_store_dwordx4 v[122:123], v[116:119], off offset:256
	v_lshl_add_u64 v[114:115], s[16:17], 0, v[114:115]
	s_and_b64 vcc, exec, s[10:11]
	v_lshl_add_u64 v[118:119], v[144:145], 2, v[114:115]
	v_mov_b32_e32 v118, v114
	v_mov_b32_e32 v119, v122
	v_mov_b32_e32 v122, v115
	v_mov_b32_e32 v114, v116
	v_mov_b32_e32 v115, v124
	v_mov_b32_e32 v124, v117
	v_pk_add_f32 v[116:117], v[118:119], v[122:123]
	v_pk_add_f32 v[114:115], v[114:115], v[124:125]
	s_nop 0
	v_pk_add_f32 v[114:115], v[116:117], v[114:115]
	s_nop 0
	v_add_f32_e32 v114, v114, v115
	v_add_f32_e32 v114, v114, v115
	v_add_f32_e32 v114, v114, v115
	v_fmamk_f32 v114, v114, 0x3a000000, v158
	v_mul_f32_e32 v115, 0x4b800000, v114
	v_cmp_gt_f32_e64 s[12:13], s57, v114
	s_nop 1
	v_cndmask_b32_e64 v114, v114, v115, s[12:13]
	s_nop 0
	v_mov_b32_e32 v114, v227
	v_pk_mul_f32 v[110:111], v[110:111], v[114:115] op_sel_hi:[1,0]
	v_pk_mul_f32 v[116:117], v[108:109], v[114:115] op_sel_hi:[1,0]
	v_pk_mul_f32 v[106:107], v[106:107], v[114:115] op_sel_hi:[1,0]
	v_pk_mul_f32 v[108:109], v[104:105], v[114:115] op_sel_hi:[1,0]
	s_cbranch_vccnz .LBB0_901
	v_mul_f32_e32 v119, v110, v110
	v_mul_f32_e32 v105, v108, v108
	v_fmamk_f32 v119, v119, 0xbdd2d3e9, v159
	v_mul_f32_e32 v122, v106, v106
	v_fmamk_f32 v105, v105, 0xbdd2d3e9, v159
	v_mul_f32_e32 v115, v117, v117
	v_mul_f32_e32 v119, v110, v119
	v_fmamk_f32 v122, v122, 0xbdd2d3e9, v159
	v_mul_f32_e32 v105, v108, v105
	v_fmamk_f32 v115, v115, 0xbdd2d3e9, v159
	v_exp_f32_e32 v119, v119
	v_mul_f32_e32 v122, v106, v122
	v_exp_f32_e32 v105, v105
	v_mul_f32_e32 v115, v117, v115
	v_exp_f32_e32 v123, v122
	v_exp_f32_e32 v115, v115
	v_add_f32_e32 v119, 1.0, v119
	v_add_f32_e32 v105, 1.0, v105
	v_rcp_f32_e32 v122, v119
	v_add_f32_e32 v119, 1.0, v123
	v_mul_f32_e32 v123, v111, v111
	v_mul_f32_e32 v104, v116, v116
	v_rcp_f32_e32 v118, v105
	v_add_f32_e32 v105, 1.0, v115
	v_mul_f32_e32 v115, v109, v109
	v_fmamk_f32 v123, v123, 0xbdd2d3e9, v159
	v_mul_f32_e32 v124, v107, v107
	v_fmamk_f32 v104, v104, 0xbdd2d3e9, v159
	v_fmamk_f32 v115, v115, 0xbdd2d3e9, v159
	v_mul_f32_e32 v123, v111, v123
	v_fmamk_f32 v124, v124, 0xbdd2d3e9, v159
	v_mul_f32_e32 v104, v116, v104
	v_mul_f32_e32 v115, v109, v115
	v_exp_f32_e32 v123, v123
	v_mul_f32_e32 v124, v107, v124
	v_exp_f32_e32 v104, v104
	v_exp_f32_e32 v115, v115
	v_exp_f32_e32 v125, v124
	v_rcp_f32_e32 v124, v119
	v_add_f32_e32 v119, 1.0, v123
	v_add_f32_e32 v104, 1.0, v104
	v_add_f32_e32 v115, 1.0, v115
	v_rcp_f32_e32 v123, v119
	v_add_f32_e32 v119, 1.0, v125
	v_rcp_f32_e32 v104, v104
	v_rcp_f32_e32 v105, v105
	v_rcp_f32_e32 v125, v119
	v_rcp_f32_e32 v119, v115
	v_pk_mul_f32 v[110:111], v[110:111], v[122:123]
	v_pk_mul_f32 v[116:117], v[116:117], v[104:105]
	v_pk_mul_f32 v[106:107], v[106:107], v[124:125]
	v_pk_mul_f32 v[108:109], v[108:109], v[118:119]

; __device__ __forceinline__ unsigned cvt_pk_bf16(float lo, float hi) { unsigned r; asm volatile("v_cvt_pk_bf16_f32 %0, %1, %2" : "=v"(r) : "v"(lo), "v"(hi)); return r; }
; __device__ __forceinline__ float gelu_tanh(float x) { const float p = __builtin_fmaf(x * x, -0.10294325f, -2.3022082f); return x * __builtin_amdgcn_rcpf(1.0f + __builtin_amdgcn_exp2f(x * p)); }
;     __device__ __forceinline__ void operator()(const f32x4 (&acc)[2][2][4][2], const Unit& u, int wr, int wc, int fr, int fq) const {
;     ...
;             for (int m = 0; m < 4; ++m) { const int row = row0 + ai * HALF + m * 16; const float rs = row_rstd(ssq, row, fr, fq);
;                 bf16_t* rowp = base + (size_t)row * 2048 + col0;
; #pragma unroll
;                 for (int bj = 0; bj < 2; ++bj) { f32x4 v0 = acc[ai][bj][m][0] * rs, v1 = acc[ai][bj][m][1] * rs;
;                     if (gate) {
; #pragma unroll
;                         for (int j = 0; j < 4; ++j) { v0[j] = gelu_tanh(v0[j]); v1[j] = gelu_tanh(v1[j]); } }
;                     u32x4 w; w.x = cvt_pk_bf16(v0[0], v0[1]); w.y = cvt_pk_bf16(v0[2], v0[3]); w.z = cvt_pk_bf16(v1[0], v1[1]); w.w = cvt_pk_bf16(v1[2], v1[3]);
;                     *(u32x4*)(rowp + bj * HALF) = w; }
.LBB0_903:
	v_cvt_pk_bf16_f32 v100, v100, v101
	v_cvt_pk_bf16_f32 v101, v102, v103
	s_nop 0
	v_cvt_pk_bf16_f32 v102, v96, v97
	v_or_b32_e32 v96, 32, v146
	v_ashrrev_i32_e32 v97, 31, v96
	v_cvt_pk_bf16_f32 v103, v98, v99
	v_lshlrev_b64 v[98:99], 7, v[96:97]
	global_store_dwordx4 v[104:105], v[100:103], off offset:256
	v_lshl_add_u64 v[98:99], s[16:17], 0, v[98:99]
	s_and_b64 vcc, exec, s[10:11]
	v_lshl_add_u64 v[102:103], v[144:145], 2, v[98:99]
	s_nop 0
	v_mov_b32_e32 v106, v98
	v_mov_b32_e32 v107, v102
	v_mov_b32_e32 v102, v99
	v_mov_b32_e32 v98, v100
	v_mov_b32_e32 v99, v104
	v_mov_b32_e32 v104, v101
	v_pk_add_f32 v[100:101], v[106:107], v[102:103]
	v_pk_add_f32 v[98:99], v[98:99], v[104:105]
	s_nop 0
	v_pk_add_f32 v[98:99], v[100:101], v[98:99]
	s_nop 0
	v_add_f32_e32 v98, v98, v99
	v_add_f32_e32 v98, v98, v99
	v_add_f32_e32 v98, v98, v99
	v_fmamk_f32 v98, v98, 0x3a000000, v158
	v_mul_f32_e32 v99, 0x4b800000, v98
	v_cmp_gt_f32_e64 s[12:13], s57, v98
	s_nop 1
	v_cndmask_b32_e64 v98, v98, v99, s[12:13]
	s_nop 0
	v_mov_b32_e32 v98, v228
	v_pk_mul_f32 v[94:95], v[94:95], v[98:99] op_sel_hi:[1,0]
	v_pk_mul_f32 v[100:101], v[92:93], v[98:99] op_sel_hi:[1,0]
	v_pk_mul_f32 v[90:91], v[90:91], v[98:99] op_sel_hi:[1,0]
	v_pk_mul_f32 v[92:93], v[88:89], v[98:99] op_sel_hi:[1,0]
	s_cbranch_vccnz .LBB0_905
	v_mul_f32_e32 v103, v94, v94
	v_mul_f32_e32 v89, v92, v92
	v_fmamk_f32 v103, v103, 0xbdd2d3e9, v159
	v_mul_f32_e32 v104, v90, v90
	v_fmamk_f32 v89, v89, 0xbdd2d3e9, v159
	v_mul_f32_e32 v99, v101, v101
	v_mul_f32_e32 v103, v94, v103
	v_fmamk_f32 v104, v104, 0xbdd2d3e9, v159
	v_mul_f32_e32 v89, v92, v89
	v_fmamk_f32 v99, v99, 0xbdd2d3e9, v159
	v_exp_f32_e32 v103, v103
	v_mul_f32_e32 v104, v90, v104
	v_exp_f32_e32 v89, v89
	v_mul_f32_e32 v99, v101, v99
	v_exp_f32_e32 v105, v104
	v_exp_f32_e32 v99, v99
	v_add_f32_e32 v103, 1.0, v103
	v_add_f32_e32 v89, 1.0, v89
	v_rcp_f32_e32 v104, v103
	v_add_f32_e32 v103, 1.0, v105
	v_mul_f32_e32 v105, v95, v95
	v_mul_f32_e32 v88, v100, v100
	v_rcp_f32_e32 v102, v89
	v_add_f32_e32 v89, 1.0, v99
	v_mul_f32_e32 v99, v93, v93
	v_fmamk_f32 v105, v105, 0xbdd2d3e9, v159
	v_mul_f32_e32 v106, v91, v91
	v_fmamk_f32 v88, v88, 0xbdd2d3e9, v159
	v_fmamk_f32 v99, v99, 0xbdd2d3e9, v159
	v_mul_f32_e32 v105, v95, v105
	v_fmamk_f32 v106, v106, 0xbdd2d3e9, v159
	v_mul_f32_e32 v88, v100, v88
	v_mul_f32_e32 v99, v93, v99
	v_exp_f32_e32 v105, v105
	v_mul_f32_e32 v106, v91, v106
	v_exp_f32_e32 v88, v88
	v_exp_f32_e32 v99, v99
	v_exp_f32_e32 v107, v106
	v_rcp_f32_e32 v106, v103
	v_add_f32_e32 v103, 1.0, v105
	v_add_f32_e32 v88, 1.0, v88
	v_add_f32_e32 v99, 1.0, v99
	v_rcp_f32_e32 v105, v103
	v_add_f32_e32 v103, 1.0, v107
	v_rcp_f32_e32 v88, v88
	v_rcp_f32_e32 v89, v89
	v_rcp_f32_e32 v107, v103
	v_rcp_f32_e32 v103, v99
	v_pk_mul_f32 v[94:95], v[94:95], v[104:105]
	v_pk_mul_f32 v[100:101], v[100:101], v[88:89]
	v_pk_mul_f32 v[90:91], v[90:91], v[106:107]
	v_pk_mul_f32 v[92:93], v[92:93], v[102:103]

; __device__ __forceinline__ unsigned cvt_pk_bf16(float lo, float hi) { unsigned r; asm volatile("v_cvt_pk_bf16_f32 %0, %1, %2" : "=v"(r) : "v"(lo), "v"(hi)); return r; }
; __device__ __forceinline__ float gelu_tanh(float x) { const float p = __builtin_fmaf(x * x, -0.10294325f, -2.3022082f); return x * __builtin_amdgcn_rcpf(1.0f + __builtin_amdgcn_exp2f(x * p)); }
;     __device__ __forceinline__ void operator()(const f32x4 (&acc)[2][2][4][2], const Unit& u, int wr, int wc, int fr, int fq) const {
;     ...
;             for (int m = 0; m < 4; ++m) { const int row = row0 + ai * HALF + m * 16; const float rs = row_rstd(ssq, row, fr, fq);
;                 bf16_t* rowp = base + (size_t)row * 2048 + col0;
; #pragma unroll
;                 for (int bj = 0; bj < 2; ++bj) { f32x4 v0 = acc[ai][bj][m][0] * rs, v1 = acc[ai][bj][m][1] * rs;
;                     if (gate) {
; #pragma unroll
;                         for (int j = 0; j < 4; ++j) { v0[j] = gelu_tanh(v0[j]); v1[j] = gelu_tanh(v1[j]); } }
;                     u32x4 w; w.x = cvt_pk_bf16(v0[0], v0[1]); w.y = cvt_pk_bf16(v0[2], v0[3]); w.z = cvt_pk_bf16(v1[0], v1[1]); w.w = cvt_pk_bf16(v1[2], v1[3]);
;                     *(u32x4*)(rowp + bj * HALF) = w; }
.LBB0_907:
	v_cvt_pk_bf16_f32 v84, v84, v85
	v_cvt_pk_bf16_f32 v85, v86, v87
	s_nop 0
	v_cvt_pk_bf16_f32 v86, v80, v81
	v_or_b32_e32 v80, 48, v146
	v_ashrrev_i32_e32 v81, 31, v80
	v_cvt_pk_bf16_f32 v87, v82, v83
	v_lshlrev_b64 v[82:83], 7, v[80:81]
	global_store_dwordx4 v[88:89], v[84:87], off offset:256
	v_lshl_add_u64 v[82:83], s[16:17], 0, v[82:83]
	s_and_b64 vcc, exec, s[10:11]
	v_lshl_add_u64 v[86:87], v[144:145], 2, v[82:83]
	s_nop 0
	v_mov_b32_e32 v90, v82
	v_mov_b32_e32 v91, v86
	v_mov_b32_e32 v86, v83
	v_mov_b32_e32 v82, v84
	v_mov_b32_e32 v83, v88
	v_mov_b32_e32 v88, v85
	v_pk_add_f32 v[84:85], v[90:91], v[86:87]
	v_pk_add_f32 v[82:83], v[82:83], v[88:89]
	s_nop 0
	v_pk_add_f32 v[82:83], v[84:85], v[82:83]
	s_nop 0
	v_add_f32_e32 v82, v82, v83
	v_add_f32_e32 v82, v82, v83
	v_add_f32_e32 v82, v82, v83
	v_fmamk_f32 v82, v82, 0x3a000000, v158
	v_mul_f32_e32 v83, 0x4b800000, v82
	v_cmp_gt_f32_e64 s[12:13], s57, v82
	s_nop 1
	v_cndmask_b32_e64 v82, v82, v83, s[12:13]
	s_nop 0
	v_mov_b32_e32 v82, v229
	v_pk_mul_f32 v[78:79], v[78:79], v[82:83] op_sel_hi:[1,0]
	v_pk_mul_f32 v[84:85], v[76:77], v[82:83] op_sel_hi:[1,0]
	v_pk_mul_f32 v[74:75], v[74:75], v[82:83] op_sel_hi:[1,0]
	v_pk_mul_f32 v[76:77], v[72:73], v[82:83] op_sel_hi:[1,0]
	s_cbranch_vccnz .LBB0_909
	v_mul_f32_e32 v87, v78, v78
	v_mul_f32_e32 v73, v76, v76
	v_fmamk_f32 v87, v87, 0xbdd2d3e9, v159
	v_mul_f32_e32 v88, v74, v74
	v_fmamk_f32 v73, v73, 0xbdd2d3e9, v159
	v_mul_f32_e32 v83, v85, v85
	v_mul_f32_e32 v87, v78, v87
	v_fmamk_f32 v88, v88, 0xbdd2d3e9, v159
	v_mul_f32_e32 v73, v76, v73
	v_fmamk_f32 v83, v83, 0xbdd2d3e9, v159
	v_exp_f32_e32 v87, v87
	v_mul_f32_e32 v88, v74, v88
	v_exp_f32_e32 v73, v73
	v_mul_f32_e32 v83, v85, v83
	v_exp_f32_e32 v89, v88
	v_exp_f32_e32 v83, v83
	v_add_f32_e32 v87, 1.0, v87
	v_add_f32_e32 v73, 1.0, v73
	v_rcp_f32_e32 v88, v87
	v_add_f32_e32 v87, 1.0, v89
	v_mul_f32_e32 v89, v79, v79
	v_mul_f32_e32 v72, v84, v84
	v_rcp_f32_e32 v86, v73
	v_add_f32_e32 v73, 1.0, v83
	v_mul_f32_e32 v83, v77, v77
	v_fmamk_f32 v89, v89, 0xbdd2d3e9, v159
	v_mul_f32_e32 v90, v75, v75
	v_fmamk_f32 v72, v72, 0xbdd2d3e9, v159
	v_fmamk_f32 v83, v83, 0xbdd2d3e9, v159
	v_mul_f32_e32 v89, v79, v89
	v_fmamk_f32 v90, v90, 0xbdd2d3e9, v159
	v_mul_f32_e32 v72, v84, v72
	v_mul_f32_e32 v83, v77, v83
	v_exp_f32_e32 v89, v89
	v_mul_f32_e32 v90, v75, v90
	v_exp_f32_e32 v72, v72
	v_exp_f32_e32 v83, v83
	v_exp_f32_e32 v91, v90
	v_rcp_f32_e32 v90, v87
	v_add_f32_e32 v87, 1.0, v89
	v_add_f32_e32 v72, 1.0, v72
	v_add_f32_e32 v83, 1.0, v83
	v_rcp_f32_e32 v89, v87
	v_add_f32_e32 v87, 1.0, v91
	v_rcp_f32_e32 v72, v72
	v_rcp_f32_e32 v73, v73
	v_rcp_f32_e32 v91, v87
	v_rcp_f32_e32 v87, v83
	v_pk_mul_f32 v[78:79], v[78:79], v[88:89]
	v_pk_mul_f32 v[84:85], v[84:85], v[72:73]
	v_pk_mul_f32 v[74:75], v[74:75], v[90:91]
	v_pk_mul_f32 v[76:77], v[76:77], v[86:87]

; __device__ __forceinline__ unsigned cvt_pk_bf16(float lo, float hi) { unsigned r; asm volatile("v_cvt_pk_bf16_f32 %0, %1, %2" : "=v"(r) : "v"(lo), "v"(hi)); return r; }
; __device__ __forceinline__ float gelu_tanh(float x) { const float p = __builtin_fmaf(x * x, -0.10294325f, -2.3022082f); return x * __builtin_amdgcn_rcpf(1.0f + __builtin_amdgcn_exp2f(x * p)); }
;     __device__ __forceinline__ void operator()(const f32x4 (&acc)[2][2][4][2], const Unit& u, int wr, int wc, int fr, int fq) const {
;     ...
;             for (int m = 0; m < 4; ++m) { const int row = row0 + ai * HALF + m * 16; const float rs = row_rstd(ssq, row, fr, fq);
;                 bf16_t* rowp = base + (size_t)row * 2048 + col0;
; #pragma unroll
;                 for (int bj = 0; bj < 2; ++bj) { f32x4 v0 = acc[ai][bj][m][0] * rs, v1 = acc[ai][bj][m][1] * rs;
;                     if (gate) {
; #pragma unroll
;                         for (int j = 0; j < 4; ++j) { v0[j] = gelu_tanh(v0[j]); v1[j] = gelu_tanh(v1[j]); } }
;                     u32x4 w; w.x = cvt_pk_bf16(v0[0], v0[1]); w.y = cvt_pk_bf16(v0[2], v0[3]); w.z = cvt_pk_bf16(v1[0], v1[1]); w.w = cvt_pk_bf16(v1[2], v1[3]);
;                     *(u32x4*)(rowp + bj * HALF) = w; }
.LBB0_911:
	v_cvt_pk_bf16_f32 v68, v68, v69
	v_cvt_pk_bf16_f32 v69, v70, v71
	s_nop 0
	v_cvt_pk_bf16_f32 v70, v64, v65
	v_add_u32_e32 v64, 0x80, v146
	v_ashrrev_i32_e32 v65, 31, v64
	v_cvt_pk_bf16_f32 v71, v66, v67
	v_lshlrev_b64 v[66:67], 7, v[64:65]
	global_store_dwordx4 v[72:73], v[68:71], off offset:256
	v_lshl_add_u64 v[66:67], s[16:17], 0, v[66:67]
	s_and_b64 vcc, exec, s[10:11]
	v_lshl_add_u64 v[70:71], v[144:145], 2, v[66:67]
	s_nop 0
	v_mov_b32_e32 v74, v66
	v_mov_b32_e32 v75, v70
	v_mov_b32_e32 v70, v67
	v_mov_b32_e32 v66, v68
	v_mov_b32_e32 v67, v72
	v_mov_b32_e32 v72, v69
	v_pk_add_f32 v[68:69], v[74:75], v[70:71]
	v_pk_add_f32 v[66:67], v[66:67], v[72:73]
	s_nop 0
	v_pk_add_f32 v[66:67], v[68:69], v[66:67]
	s_nop 0
	v_add_f32_e32 v66, v66, v67
	v_add_f32_e32 v66, v66, v67
	v_add_f32_e32 v66, v66, v67
	v_fmamk_f32 v66, v66, 0x3a000000, v158
	v_mul_f32_e32 v67, 0x4b800000, v66
	v_cmp_gt_f32_e64 s[12:13], s57, v66
	s_nop 1
	v_cndmask_b32_e64 v66, v66, v67, s[12:13]
	s_nop 0
	v_mov_b32_e32 v66, v230
	v_pk_mul_f32 v[62:63], v[62:63], v[66:67] op_sel_hi:[1,0]
	v_pk_mul_f32 v[68:69], v[60:61], v[66:67] op_sel_hi:[1,0]
	v_pk_mul_f32 v[58:59], v[58:59], v[66:67] op_sel_hi:[1,0]
	v_pk_mul_f32 v[60:61], v[56:57], v[66:67] op_sel_hi:[1,0]
	s_cbranch_vccnz .LBB0_913
	v_mul_f32_e32 v71, v62, v62
	v_mul_f32_e32 v57, v60, v60
	v_fmamk_f32 v71, v71, 0xbdd2d3e9, v159
	v_mul_f32_e32 v72, v58, v58
	v_fmamk_f32 v57, v57, 0xbdd2d3e9, v159
	v_mul_f32_e32 v67, v69, v69
	v_mul_f32_e32 v71, v62, v71
	v_fmamk_f32 v72, v72, 0xbdd2d3e9, v159
	v_mul_f32_e32 v57, v60, v57
	v_fmamk_f32 v67, v67, 0xbdd2d3e9, v159
	v_exp_f32_e32 v71, v71
	v_mul_f32_e32 v72, v58, v72
	v_exp_f32_e32 v57, v57
	v_mul_f32_e32 v67, v69, v67
	v_exp_f32_e32 v73, v72
	v_exp_f32_e32 v67, v67
	v_add_f32_e32 v71, 1.0, v71
	v_add_f32_e32 v57, 1.0, v57
	v_rcp_f32_e32 v72, v71
	v_add_f32_e32 v71, 1.0, v73
	v_mul_f32_e32 v73, v63, v63
	v_mul_f32_e32 v56, v68, v68
	v_rcp_f32_e32 v70, v57
	v_add_f32_e32 v57, 1.0, v67
	v_mul_f32_e32 v67, v61, v61
	v_fmamk_f32 v73, v73, 0xbdd2d3e9, v159
	v_mul_f32_e32 v74, v59, v59
	v_fmamk_f32 v56, v56, 0xbdd2d3e9, v159
	v_fmamk_f32 v67, v67, 0xbdd2d3e9, v159
	v_mul_f32_e32 v73, v63, v73
	v_fmamk_f32 v74, v74, 0xbdd2d3e9, v159
	v_mul_f32_e32 v56, v68, v56
	v_mul_f32_e32 v67, v61, v67
	v_exp_f32_e32 v73, v73
	v_mul_f32_e32 v74, v59, v74
	v_exp_f32_e32 v56, v56
	v_exp_f32_e32 v67, v67
	v_exp_f32_e32 v75, v74
	v_rcp_f32_e32 v74, v71
	v_add_f32_e32 v71, 1.0, v73
	v_add_f32_e32 v56, 1.0, v56
	v_add_f32_e32 v67, 1.0, v67
	v_rcp_f32_e32 v73, v71
	v_add_f32_e32 v71, 1.0, v75
	v_rcp_f32_e32 v56, v56
	v_rcp_f32_e32 v57, v57
	v_rcp_f32_e32 v75, v71
	v_rcp_f32_e32 v71, v67
	v_pk_mul_f32 v[62:63], v[62:63], v[72:73]
	v_pk_mul_f32 v[68:69], v[68:69], v[56:57]
	v_pk_mul_f32 v[58:59], v[58:59], v[74:75]
	v_pk_mul_f32 v[60:61], v[60:61], v[70:71]

; __device__ __forceinline__ unsigned cvt_pk_bf16(float lo, float hi) { unsigned r; asm volatile("v_cvt_pk_bf16_f32 %0, %1, %2" : "=v"(r) : "v"(lo), "v"(hi)); return r; }
; __device__ __forceinline__ float gelu_tanh(float x) { const float p = __builtin_fmaf(x * x, -0.10294325f, -2.3022082f); return x * __builtin_amdgcn_rcpf(1.0f + __builtin_amdgcn_exp2f(x * p)); }
;     __device__ __forceinline__ void operator()(const f32x4 (&acc)[2][2][4][2], const Unit& u, int wr, int wc, int fr, int fq) const {
;     ...
;             for (int m = 0; m < 4; ++m) { const int row = row0 + ai * HALF + m * 16; const float rs = row_rstd(ssq, row, fr, fq);
;                 bf16_t* rowp = base + (size_t)row * 2048 + col0;
; #pragma unroll
;                 for (int bj = 0; bj < 2; ++bj) { f32x4 v0 = acc[ai][bj][m][0] * rs, v1 = acc[ai][bj][m][1] * rs;
;                     if (gate) {
; #pragma unroll
;                         for (int j = 0; j < 4; ++j) { v0[j] = gelu_tanh(v0[j]); v1[j] = gelu_tanh(v1[j]); } }
;                     u32x4 w; w.x = cvt_pk_bf16(v0[0], v0[1]); w.y = cvt_pk_bf16(v0[2], v0[3]); w.z = cvt_pk_bf16(v1[0], v1[1]); w.w = cvt_pk_bf16(v1[2], v1[3]);
;                     *(u32x4*)(rowp + bj * HALF) = w; }
.LBB0_915:
	v_cvt_pk_bf16_f32 v52, v52, v53
	v_cvt_pk_bf16_f32 v53, v54, v55
	s_nop 0
	v_cvt_pk_bf16_f32 v54, v48, v49
	v_add_u32_e32 v48, 0x90, v146
	v_ashrrev_i32_e32 v49, 31, v48
	v_cvt_pk_bf16_f32 v55, v50, v51
	v_lshlrev_b64 v[50:51], 7, v[48:49]
	global_store_dwordx4 v[56:57], v[52:55], off offset:256
	v_lshl_add_u64 v[50:51], s[16:17], 0, v[50:51]
	s_and_b64 vcc, exec, s[10:11]
	v_lshl_add_u64 v[54:55], v[144:145], 2, v[50:51]
	s_nop 0
	v_mov_b32_e32 v58, v50
	v_mov_b32_e32 v59, v54
	v_mov_b32_e32 v54, v51
	v_mov_b32_e32 v50, v52
	v_mov_b32_e32 v51, v56
	v_mov_b32_e32 v56, v53
	v_pk_add_f32 v[52:53], v[58:59], v[54:55]
	v_pk_add_f32 v[50:51], v[50:51], v[56:57]
	s_nop 0
	v_pk_add_f32 v[50:51], v[52:53], v[50:51]
	s_nop 0
	v_add_f32_e32 v50, v50, v51
	v_add_f32_e32 v50, v50, v51
	v_add_f32_e32 v50, v50, v51
	v_fmamk_f32 v50, v50, 0x3a000000, v158
	v_mul_f32_e32 v51, 0x4b800000, v50
	v_cmp_gt_f32_e64 s[12:13], s57, v50
	s_nop 1
	v_cndmask_b32_e64 v50, v50, v51, s[12:13]
	s_nop 0
	v_mov_b32_e32 v50, v231
	v_pk_mul_f32 v[46:47], v[46:47], v[50:51] op_sel_hi:[1,0]
	v_pk_mul_f32 v[52:53], v[44:45], v[50:51] op_sel_hi:[1,0]
	v_pk_mul_f32 v[42:43], v[42:43], v[50:51] op_sel_hi:[1,0]
	v_pk_mul_f32 v[44:45], v[40:41], v[50:51] op_sel_hi:[1,0]
	s_cbranch_vccnz .LBB0_917
	v_mul_f32_e32 v55, v46, v46
	v_mul_f32_e32 v41, v44, v44
	v_fmamk_f32 v55, v55, 0xbdd2d3e9, v159
	v_mul_f32_e32 v56, v42, v42
	v_fmamk_f32 v41, v41, 0xbdd2d3e9, v159
	v_mul_f32_e32 v51, v53, v53
	v_mul_f32_e32 v55, v46, v55
	v_fmamk_f32 v56, v56, 0xbdd2d3e9, v159
	v_mul_f32_e32 v41, v44, v41
	v_fmamk_f32 v51, v51, 0xbdd2d3e9, v159
	v_exp_f32_e32 v55, v55
	v_mul_f32_e32 v56, v42, v56
	v_exp_f32_e32 v41, v41
	v_mul_f32_e32 v51, v53, v51
	v_exp_f32_e32 v57, v56
	v_exp_f32_e32 v51, v51
	v_add_f32_e32 v55, 1.0, v55
	v_add_f32_e32 v41, 1.0, v41
	v_rcp_f32_e32 v56, v55
	v_add_f32_e32 v55, 1.0, v57
	v_mul_f32_e32 v57, v47, v47
	v_mul_f32_e32 v40, v52, v52
	v_rcp_f32_e32 v54, v41
	v_add_f32_e32 v41, 1.0, v51
	v_mul_f32_e32 v51, v45, v45
	v_fmamk_f32 v57, v57, 0xbdd2d3e9, v159
	v_mul_f32_e32 v58, v43, v43
	v_fmamk_f32 v40, v40, 0xbdd2d3e9, v159
	v_fmamk_f32 v51, v51, 0xbdd2d3e9, v159
	v_mul_f32_e32 v57, v47, v57
	v_fmamk_f32 v58, v58, 0xbdd2d3e9, v159
	v_mul_f32_e32 v40, v52, v40
	v_mul_f32_e32 v51, v45, v51
	v_exp_f32_e32 v57, v57
	v_mul_f32_e32 v58, v43, v58
	v_exp_f32_e32 v40, v40
	v_exp_f32_e32 v51, v51
	v_exp_f32_e32 v59, v58
	v_rcp_f32_e32 v58, v55
	v_add_f32_e32 v55, 1.0, v57
	v_add_f32_e32 v40, 1.0, v40
	v_add_f32_e32 v51, 1.0, v51
	v_rcp_f32_e32 v57, v55
	v_add_f32_e32 v55, 1.0, v59
	v_rcp_f32_e32 v40, v40
	v_rcp_f32_e32 v41, v41
	v_rcp_f32_e32 v59, v55
	v_rcp_f32_e32 v55, v51
	v_pk_mul_f32 v[46:47], v[46:47], v[56:57]
	v_pk_mul_f32 v[52:53], v[52:53], v[40:41]
	v_pk_mul_f32 v[42:43], v[42:43], v[58:59]
	v_pk_mul_f32 v[44:45], v[44:45], v[54:55]

; __device__ __forceinline__ unsigned cvt_pk_bf16(float lo, float hi) { unsigned r; asm volatile("v_cvt_pk_bf16_f32 %0, %1, %2" : "=v"(r) : "v"(lo), "v"(hi)); return r; }
; __device__ __forceinline__ float gelu_tanh(float x) { const float p = __builtin_fmaf(x * x, -0.10294325f, -2.3022082f); return x * __builtin_amdgcn_rcpf(1.0f + __builtin_amdgcn_exp2f(x * p)); }
;     __device__ __forceinline__ void operator()(const f32x4 (&acc)[2][2][4][2], const Unit& u, int wr, int wc, int fr, int fq) const {
;     ...
;             for (int m = 0; m < 4; ++m) { const int row = row0 + ai * HALF + m * 16; const float rs = row_rstd(ssq, row, fr, fq);
;                 bf16_t* rowp = base + (size_t)row * 2048 + col0;
; #pragma unroll
;                 for (int bj = 0; bj < 2; ++bj) { f32x4 v0 = acc[ai][bj][m][0] * rs, v1 = acc[ai][bj][m][1] * rs;
;                     if (gate) {
; #pragma unroll
;                         for (int j = 0; j < 4; ++j) { v0[j] = gelu_tanh(v0[j]); v1[j] = gelu_tanh(v1[j]); } }
;                     u32x4 w; w.x = cvt_pk_bf16(v0[0], v0[1]); w.y = cvt_pk_bf16(v0[2], v0[3]); w.z = cvt_pk_bf16(v1[0], v1[1]); w.w = cvt_pk_bf16(v1[2], v1[3]);
;                     *(u32x4*)(rowp + bj * HALF) = w; }
.LBB0_919:
	v_cvt_pk_bf16_f32 v36, v36, v37
	v_cvt_pk_bf16_f32 v37, v38, v39
	s_nop 0
	v_cvt_pk_bf16_f32 v38, v32, v33
	v_add_u32_e32 v32, 0xa0, v146
	v_ashrrev_i32_e32 v33, 31, v32
	v_cvt_pk_bf16_f32 v39, v34, v35
	v_lshlrev_b64 v[34:35], 7, v[32:33]
	global_store_dwordx4 v[40:41], v[36:39], off offset:256
	v_lshl_add_u64 v[34:35], s[16:17], 0, v[34:35]
	s_and_b64 vcc, exec, s[10:11]
	v_lshl_add_u64 v[38:39], v[144:145], 2, v[34:35]
	s_nop 0
	v_mov_b32_e32 v42, v34
	v_mov_b32_e32 v43, v38
	v_mov_b32_e32 v38, v35
	v_mov_b32_e32 v34, v36
	v_mov_b32_e32 v35, v40
	v_mov_b32_e32 v40, v37
	v_pk_add_f32 v[36:37], v[42:43], v[38:39]
	v_pk_add_f32 v[34:35], v[34:35], v[40:41]
	s_nop 0
	v_pk_add_f32 v[34:35], v[36:37], v[34:35]
	s_nop 0
	v_add_f32_e32 v34, v34, v35
	v_add_f32_e32 v34, v34, v35
	v_add_f32_e32 v34, v34, v35
	v_fmamk_f32 v34, v34, 0x3a000000, v158
	v_mul_f32_e32 v35, 0x4b800000, v34
	v_cmp_gt_f32_e64 s[12:13], s57, v34
	s_nop 1
	v_cndmask_b32_e64 v34, v34, v35, s[12:13]
	s_nop 0
	v_mov_b32_e32 v34, v232
	v_pk_mul_f32 v[30:31], v[30:31], v[34:35] op_sel_hi:[1,0]
	v_pk_mul_f32 v[36:37], v[28:29], v[34:35] op_sel_hi:[1,0]
	v_pk_mul_f32 v[26:27], v[26:27], v[34:35] op_sel_hi:[1,0]
	v_pk_mul_f32 v[28:29], v[24:25], v[34:35] op_sel_hi:[1,0]
	s_cbranch_vccnz .LBB0_921
	v_mul_f32_e32 v39, v30, v30
	v_mul_f32_e32 v25, v28, v28
	v_fmamk_f32 v39, v39, 0xbdd2d3e9, v159
	v_mul_f32_e32 v40, v26, v26
	v_fmamk_f32 v25, v25, 0xbdd2d3e9, v159
	v_mul_f32_e32 v35, v37, v37
	v_mul_f32_e32 v39, v30, v39
	v_fmamk_f32 v40, v40, 0xbdd2d3e9, v159
	v_mul_f32_e32 v25, v28, v25
	v_fmamk_f32 v35, v35, 0xbdd2d3e9, v159
	v_exp_f32_e32 v39, v39
	v_mul_f32_e32 v40, v26, v40
	v_exp_f32_e32 v25, v25
	v_mul_f32_e32 v35, v37, v35
	v_exp_f32_e32 v41, v40
	v_exp_f32_e32 v35, v35
	v_add_f32_e32 v39, 1.0, v39
	v_add_f32_e32 v25, 1.0, v25
	v_rcp_f32_e32 v40, v39
	v_add_f32_e32 v39, 1.0, v41
	v_mul_f32_e32 v41, v31, v31
	v_mul_f32_e32 v24, v36, v36
	v_rcp_f32_e32 v38, v25
	v_add_f32_e32 v25, 1.0, v35
	v_mul_f32_e32 v35, v29, v29
	v_fmamk_f32 v41, v41, 0xbdd2d3e9, v159
	v_mul_f32_e32 v42, v27, v27
	v_fmamk_f32 v24, v24, 0xbdd2d3e9, v159
	v_fmamk_f32 v35, v35, 0xbdd2d3e9, v159
	v_mul_f32_e32 v41, v31, v41
	v_fmamk_f32 v42, v42, 0xbdd2d3e9, v159
	v_mul_f32_e32 v24, v36, v24
	v_mul_f32_e32 v35, v29, v35
	v_exp_f32_e32 v41, v41
	v_mul_f32_e32 v42, v27, v42
	v_exp_f32_e32 v24, v24
	v_exp_f32_e32 v35, v35
	v_exp_f32_e32 v43, v42
	v_rcp_f32_e32 v42, v39
	v_add_f32_e32 v39, 1.0, v41
	v_add_f32_e32 v24, 1.0, v24
	v_add_f32_e32 v35, 1.0, v35
	v_rcp_f32_e32 v41, v39
	v_add_f32_e32 v39, 1.0, v43
	v_rcp_f32_e32 v24, v24
	v_rcp_f32_e32 v25, v25
	v_rcp_f32_e32 v43, v39
	v_rcp_f32_e32 v39, v35
	v_pk_mul_f32 v[30:31], v[30:31], v[40:41]
	v_pk_mul_f32 v[36:37], v[36:37], v[24:25]
	v_pk_mul_f32 v[26:27], v[26:27], v[42:43]
	v_pk_mul_f32 v[28:29], v[28:29], v[38:39]

; __device__ __forceinline__ unsigned cvt_pk_bf16(float lo, float hi) { unsigned r; asm volatile("v_cvt_pk_bf16_f32 %0, %1, %2" : "=v"(r) : "v"(lo), "v"(hi)); return r; }
; __device__ __forceinline__ float gelu_tanh(float x) { const float p = __builtin_fmaf(x * x, -0.10294325f, -2.3022082f); return x * __builtin_amdgcn_rcpf(1.0f + __builtin_amdgcn_exp2f(x * p)); }
;     __device__ __forceinline__ void operator()(const f32x4 (&acc)[2][2][4][2], const Unit& u, int wr, int wc, int fr, int fq) const {
;     ...
;             for (int m = 0; m < 4; ++m) { const int row = row0 + ai * HALF + m * 16; const float rs = row_rstd(ssq, row, fr, fq);
;                 bf16_t* rowp = base + (size_t)row * 2048 + col0;
; #pragma unroll
;                 for (int bj = 0; bj < 2; ++bj) { f32x4 v0 = acc[ai][bj][m][0] * rs, v1 = acc[ai][bj][m][1] * rs;
;                     if (gate) {
; #pragma unroll
;                         for (int j = 0; j < 4; ++j) { v0[j] = gelu_tanh(v0[j]); v1[j] = gelu_tanh(v1[j]); } }
;                     u32x4 w; w.x = cvt_pk_bf16(v0[0], v0[1]); w.y = cvt_pk_bf16(v0[2], v0[3]); w.z = cvt_pk_bf16(v1[0], v1[1]); w.w = cvt_pk_bf16(v1[2], v1[3]);
;                     *(u32x4*)(rowp + bj * HALF) = w; }
.LBB0_923:
	v_cvt_pk_bf16_f32 v20, v20, v21
	v_cvt_pk_bf16_f32 v21, v22, v23
	s_nop 0
	v_cvt_pk_bf16_f32 v22, v16, v17
	v_add_u32_e32 v16, 0xb0, v146
	v_ashrrev_i32_e32 v17, 31, v16
	v_cvt_pk_bf16_f32 v23, v18, v19
	v_lshlrev_b64 v[18:19], 7, v[16:17]
	global_store_dwordx4 v[24:25], v[20:23], off offset:256
	v_lshl_add_u64 v[18:19], s[16:17], 0, v[18:19]
	s_and_b64 vcc, exec, s[10:11]
	v_lshl_add_u64 v[22:23], v[144:145], 2, v[18:19]
	s_nop 0
	v_mov_b32_e32 v26, v18
	v_mov_b32_e32 v27, v22
	v_mov_b32_e32 v22, v19
	v_mov_b32_e32 v18, v20
	v_mov_b32_e32 v19, v24
	v_mov_b32_e32 v24, v21
	v_pk_add_f32 v[20:21], v[26:27], v[22:23]
	v_pk_add_f32 v[18:19], v[18:19], v[24:25]
	s_nop 0
	v_pk_add_f32 v[18:19], v[20:21], v[18:19]
	s_nop 0
	v_add_f32_e32 v18, v18, v19
	v_add_f32_e32 v18, v18, v19
	v_add_f32_e32 v18, v18, v19
	v_fmamk_f32 v18, v18, 0x3a000000, v158
	v_mul_f32_e32 v19, 0x4b800000, v18
	v_cmp_gt_f32_e64 s[12:13], s57, v18
	s_nop 1
	v_cndmask_b32_e64 v18, v18, v19, s[12:13]
	s_nop 0
	v_mov_b32_e32 v18, v233
	v_pk_mul_f32 v[14:15], v[14:15], v[18:19] op_sel_hi:[1,0]
	v_pk_mul_f32 v[20:21], v[12:13], v[18:19] op_sel_hi:[1,0]
	v_pk_mul_f32 v[10:11], v[10:11], v[18:19] op_sel_hi:[1,0]
	v_pk_mul_f32 v[12:13], v[8:9], v[18:19] op_sel_hi:[1,0]
	s_cbranch_vccnz .LBB0_925
	v_mul_f32_e32 v23, v14, v14
	v_mul_f32_e32 v9, v12, v12
	v_fmamk_f32 v23, v23, 0xbdd2d3e9, v159
	v_mul_f32_e32 v24, v10, v10
	v_fmamk_f32 v9, v9, 0xbdd2d3e9, v159
	v_mul_f32_e32 v19, v21, v21
	v_mul_f32_e32 v23, v14, v23
	v_fmamk_f32 v24, v24, 0xbdd2d3e9, v159
	v_mul_f32_e32 v9, v12, v9
	v_fmamk_f32 v19, v19, 0xbdd2d3e9, v159
	v_exp_f32_e32 v23, v23
	v_mul_f32_e32 v24, v10, v24
	v_exp_f32_e32 v9, v9
	v_mul_f32_e32 v19, v21, v19
	v_exp_f32_e32 v25, v24
	v_exp_f32_e32 v19, v19
	v_add_f32_e32 v23, 1.0, v23
	v_add_f32_e32 v9, 1.0, v9
	v_rcp_f32_e32 v24, v23
	v_add_f32_e32 v23, 1.0, v25
	v_mul_f32_e32 v25, v15, v15
	v_mul_f32_e32 v8, v20, v20
	v_rcp_f32_e32 v22, v9
	v_add_f32_e32 v9, 1.0, v19
	v_mul_f32_e32 v19, v13, v13
	v_fmamk_f32 v25, v25, 0xbdd2d3e9, v159
	v_mul_f32_e32 v26, v11, v11
	v_fmamk_f32 v8, v8, 0xbdd2d3e9, v159
	v_fmamk_f32 v19, v19, 0xbdd2d3e9, v159
	v_mul_f32_e32 v25, v15, v25
	v_fmamk_f32 v26, v26, 0xbdd2d3e9, v159
	v_mul_f32_e32 v8, v20, v8
	v_mul_f32_e32 v19, v13, v19
	v_exp_f32_e32 v25, v25
	v_mul_f32_e32 v26, v11, v26
	v_exp_f32_e32 v8, v8
	v_exp_f32_e32 v19, v19
	v_exp_f32_e32 v27, v26
	v_rcp_f32_e32 v26, v23
	v_add_f32_e32 v23, 1.0, v25
	v_add_f32_e32 v8, 1.0, v8
	v_add_f32_e32 v19, 1.0, v19
	v_rcp_f32_e32 v25, v23
	v_add_f32_e32 v23, 1.0, v27
	v_rcp_f32_e32 v8, v8
	v_rcp_f32_e32 v9, v9
	v_rcp_f32_e32 v27, v23
	v_rcp_f32_e32 v23, v19
	v_pk_mul_f32 v[14:15], v[14:15], v[24:25]
	v_pk_mul_f32 v[20:21], v[20:21], v[8:9]
	v_pk_mul_f32 v[10:11], v[10:11], v[26:27]
	v_pk_mul_f32 v[12:13], v[12:13], v[22:23]
